# removed the GEMM phases per-cluster s_setprio flips; LRU gate GEMM fragment reads pipelined with hoisted LDS addresses; attention even-step K fragment reads pipelined
# speedup vs baseline: 1.0384x; 1.0040x over previous
.LBB0_177:
	ds_read_b128 v[128:131], v171
	ds_read_b128 v[132:135], v171 offset:1024
	ds_read_b128 v[136:139], v171 offset:2048
	ds_read_b128 v[160:163], v171 offset:3072
	ds_read_b128 v[164:167], v172
	ds_read_b128 v[174:177], v172 offset:1024
	ds_read_b128 v[178:181], v172 offset:2048
	ds_read_b128 v[182:185], v172 offset:3072
	s_add_u32 s52, s44, 0xfffc0080
	s_addc_u32 s53, s45, -1
	s_cmp_eq_u32 s84, 12
	s_cselect_b32 s57, s7, s53
	s_cselect_b32 s56, s8, s52
	s_cselect_b32 s53, s27, s83
	s_cselect_b32 s52, s29, s43
	v_lshl_add_u64 v[198:199], s[44:45], 0, v[152:153]
	s_add_i32 m0, s33, 0xc000
	ds_read_b128 v[186:189], v173
	ds_read_b128 v[190:193], v173 offset:1024
	ds_read_b128 v[194:197], v173 offset:2048
	ds_read_b128 v[202:205], v173 offset:3072
	ds_read_b128 v[206:209], v173 offset:4096
	ds_read_b128 v[210:213], v173 offset:5120
	ds_read_b128 v[214:217], v173 offset:6144
	ds_read_b128 v[218:221], v173 offset:7168
	global_load_lds_dwordx4 v[198:199], off
	v_lshl_add_u64 v[198:199], s[44:45], 0, v[154:155]
	s_add_i32 m0, s33, 0xe000
	s_nop 0
	global_load_lds_dwordx4 v[198:199], off
	s_waitcnt vmcnt(8)
	s_waitcnt lgkmcnt(0)
	s_barrier
	s_waitcnt lgkmcnt(0)
	v_mfma_f32_16x16x32_bf16 v[124:127], v[128:131], v[186:189], v[124:127]
	v_mfma_f32_16x16x32_bf16 v[120:123], v[136:139], v[186:189], v[120:123]
	v_mfma_f32_16x16x32_bf16 v[112:115], v[128:131], v[194:197], v[112:115]
	v_mfma_f32_16x16x32_bf16 v[104:107], v[136:139], v[194:197], v[104:107]
	v_mfma_f32_16x16x32_bf16 v[100:103], v[128:131], v[206:209], v[100:103]
	v_mfma_f32_16x16x32_bf16 v[92:95], v[136:139], v[206:209], v[92:95]
	v_mfma_f32_16x16x32_bf16 v[84:87], v[128:131], v[214:217], v[84:87]
	v_mfma_f32_16x16x32_bf16 v[76:79], v[136:139], v[214:217], v[76:79]
	v_mfma_f32_16x16x32_bf16 v[124:127], v[132:135], v[190:193], v[124:127]
	v_mfma_f32_16x16x32_bf16 v[120:123], v[160:163], v[190:193], v[120:123]
	v_mfma_f32_16x16x32_bf16 v[112:115], v[132:135], v[202:205], v[112:115]
	v_mfma_f32_16x16x32_bf16 v[104:107], v[160:163], v[202:205], v[104:107]
	v_mfma_f32_16x16x32_bf16 v[100:103], v[132:135], v[210:213], v[100:103]
	v_mfma_f32_16x16x32_bf16 v[92:95], v[160:163], v[210:213], v[92:95]
	v_mfma_f32_16x16x32_bf16 v[84:87], v[132:135], v[218:221], v[84:87]
	v_mfma_f32_16x16x32_bf16 v[76:79], v[160:163], v[218:221], v[76:79]
	v_mfma_f32_16x16x32_bf16 v[116:119], v[164:167], v[186:189], v[116:119]
	v_mfma_f32_16x16x32_bf16 v[108:111], v[178:181], v[186:189], v[108:111]
	v_mfma_f32_16x16x32_bf16 v[96:99], v[164:167], v[194:197], v[96:99]
	v_mfma_f32_16x16x32_bf16 v[88:91], v[178:181], v[194:197], v[88:91]
	v_mfma_f32_16x16x32_bf16 v[80:83], v[164:167], v[206:209], v[80:83]
	v_mfma_f32_16x16x32_bf16 v[72:75], v[178:181], v[206:209], v[72:75]
	v_mfma_f32_16x16x32_bf16 v[68:71], v[164:167], v[214:217], v[68:71]
	v_mfma_f32_16x16x32_bf16 v[64:67], v[178:181], v[214:217], v[64:67]
	v_mfma_f32_16x16x32_bf16 v[116:119], v[174:177], v[190:193], v[116:119]
	v_mfma_f32_16x16x32_bf16 v[108:111], v[182:185], v[190:193], v[108:111]
	v_mfma_f32_16x16x32_bf16 v[96:99], v[174:177], v[202:205], v[96:99]
	v_mfma_f32_16x16x32_bf16 v[88:91], v[182:185], v[202:205], v[88:91]
	v_mfma_f32_16x16x32_bf16 v[80:83], v[174:177], v[210:213], v[80:83]
	v_mfma_f32_16x16x32_bf16 v[72:75], v[182:185], v[210:213], v[72:75]
	v_mfma_f32_16x16x32_bf16 v[68:71], v[174:177], v[218:221], v[68:71]
	v_mfma_f32_16x16x32_bf16 v[64:67], v[182:185], v[218:221], v[64:67]
	s_barrier
	s_add_i32 s85, s80, s3
	v_lshl_add_u64 v[198:199], s[52:53], 0, v[142:143]
	s_mov_b32 m0, s85
	ds_read_b128 v[186:189], v173 offset:16384
	ds_read_b128 v[190:193], v173 offset:17408
	ds_read_b128 v[194:197], v173 offset:18432
	ds_read_b128 v[202:205], v173 offset:19456
	ds_read_b128 v[206:209], v173 offset:20480
	ds_read_b128 v[210:213], v173 offset:21504
	ds_read_b128 v[214:217], v173 offset:22528
	ds_read_b128 v[218:221], v173 offset:23552
	global_load_lds_dwordx4 v[198:199], off
	s_add_i32 m0, s85, 0x2000
	s_add_u32 s86, s52, 0x40000
	v_lshl_add_u64 v[200:201], s[52:53], 0, v[146:147]
	s_addc_u32 s87, s53, 0
	s_add_i32 s85, s81, s3
	global_load_lds_dwordx4 v[200:201], off
	v_lshl_add_u64 v[222:223], s[86:87], 0, v[142:143]
	s_mov_b32 m0, s85
	v_lshl_add_u64 v[224:225], s[56:57], 0, v[144:145]
	global_load_lds_dwordx4 v[222:223], off
	v_lshl_add_u64 v[222:223], s[86:87], 0, v[146:147]
	s_add_i32 m0, s85, 0x2000
	s_nop 0
	global_load_lds_dwordx4 v[222:223], off
	v_lshl_add_u64 v[222:223], s[56:57], 0, v[140:141]
	s_mov_b32 m0, s33
	s_nop 0
	global_load_lds_dwordx4 v[222:223], off
	s_mov_b32 m0, s62
	s_nop 0
	global_load_lds_dwordx4 v[224:225], off
	s_waitcnt vmcnt(8)
	s_waitcnt lgkmcnt(0)
	s_barrier
	s_waitcnt lgkmcnt(0)
	v_mfma_f32_16x16x32_bf16 v[60:63], v[128:131], v[186:189], v[60:63]
	v_mfma_f32_16x16x32_bf16 v[56:59], v[136:139], v[186:189], v[56:59]
	v_mfma_f32_16x16x32_bf16 v[52:55], v[128:131], v[194:197], v[52:55]
	v_mfma_f32_16x16x32_bf16 v[44:47], v[136:139], v[194:197], v[44:47]
	v_mfma_f32_16x16x32_bf16 v[36:39], v[128:131], v[206:209], v[36:39]
	v_mfma_f32_16x16x32_bf16 v[28:31], v[136:139], v[206:209], v[28:31]
	v_mfma_f32_16x16x32_bf16 v[20:23], v[128:131], v[214:217], v[20:23]
	v_mfma_f32_16x16x32_bf16 v[12:15], v[136:139], v[214:217], v[12:15]
	v_mfma_f32_16x16x32_bf16 v[60:63], v[132:135], v[190:193], v[60:63]
	v_mfma_f32_16x16x32_bf16 v[56:59], v[160:163], v[190:193], v[56:59]
	v_mfma_f32_16x16x32_bf16 v[52:55], v[132:135], v[202:205], v[52:55]
	v_mfma_f32_16x16x32_bf16 v[44:47], v[160:163], v[202:205], v[44:47]
	v_mfma_f32_16x16x32_bf16 v[36:39], v[132:135], v[210:213], v[36:39]
	v_mfma_f32_16x16x32_bf16 v[28:31], v[160:163], v[210:213], v[28:31]
	v_mfma_f32_16x16x32_bf16 v[20:23], v[132:135], v[218:221], v[20:23]
	v_mfma_f32_16x16x32_bf16 v[12:15], v[160:163], v[218:221], v[12:15]
	v_mfma_f32_16x16x32_bf16 v[48:51], v[164:167], v[186:189], v[48:51]
	v_mfma_f32_16x16x32_bf16 v[40:43], v[178:181], v[186:189], v[40:43]
	v_mfma_f32_16x16x32_bf16 v[32:35], v[164:167], v[194:197], v[32:35]
	v_mfma_f32_16x16x32_bf16 v[24:27], v[178:181], v[194:197], v[24:27]
	v_mfma_f32_16x16x32_bf16 v[16:19], v[164:167], v[206:209], v[16:19]
	v_mfma_f32_16x16x32_bf16 v[8:11], v[178:181], v[206:209], v[8:11]
	v_mfma_f32_16x16x32_bf16 v[4:7], v[164:167], v[214:217], v[4:7]
	v_mfma_f32_16x16x32_bf16 v[0:3], v[178:181], v[214:217], v[0:3]
	v_mfma_f32_16x16x32_bf16 v[48:51], v[174:177], v[190:193], v[48:51]
	v_mfma_f32_16x16x32_bf16 v[40:43], v[182:185], v[190:193], v[40:43]
	v_mfma_f32_16x16x32_bf16 v[32:35], v[174:177], v[202:205], v[32:35]
	v_mfma_f32_16x16x32_bf16 v[24:27], v[182:185], v[202:205], v[24:27]
	v_mfma_f32_16x16x32_bf16 v[16:19], v[174:177], v[210:213], v[16:19]
	v_mfma_f32_16x16x32_bf16 v[8:11], v[182:185], v[210:213], v[8:11]
	v_mfma_f32_16x16x32_bf16 v[4:7], v[174:177], v[218:221], v[4:7]
	v_mfma_f32_16x16x32_bf16 v[0:3], v[182:185], v[218:221], v[0:3]
	s_barrier
	s_add_i32 s85, 0, 0x18000
	v_add_u32_e32 v148, s85, v169
	s_add_i32 s86, 0, 0x1c000
	ds_read_b128 v[128:131], v148
	ds_read_b128 v[132:135], v148 offset:1024
	ds_read_b128 v[136:139], v148 offset:2048
	ds_read_b128 v[160:163], v148 offset:3072
	v_add_u32_e32 v148, s86, v169
	ds_read_b128 v[164:167], v148
	ds_read_b128 v[174:177], v148 offset:1024
	ds_read_b128 v[178:181], v148 offset:2048
	ds_read_b128 v[182:185], v148 offset:3072
	s_add_u32 s56, s56, 0x40000
	s_addc_u32 s57, s57, 0
	s_mov_b32 m0, s63
	v_lshl_add_u64 v[226:227], s[56:57], 0, v[140:141]
	ds_read_b128 v[186:189], v173 offset:32768
	ds_read_b128 v[190:193], v173 offset:33792
	ds_read_b128 v[194:197], v173 offset:34816
	ds_read_b128 v[202:205], v173 offset:35840
	ds_read_b128 v[206:209], v173 offset:36864
	ds_read_b128 v[210:213], v173 offset:37888
	ds_read_b128 v[214:217], v173 offset:38912
	ds_read_b128 v[218:221], v173 offset:39936
	global_load_lds_dwordx4 v[226:227], off
	v_lshl_add_u64 v[226:227], s[56:57], 0, v[144:145]
	s_mov_b32 m0, s64
	s_nop 0
	global_load_lds_dwordx4 v[226:227], off
	s_waitcnt vmcnt(8)
	s_waitcnt lgkmcnt(0)
	s_barrier
	s_waitcnt lgkmcnt(0)
	v_mfma_f32_16x16x32_bf16 v[124:127], v[128:131], v[186:189], v[124:127]
	v_mfma_f32_16x16x32_bf16 v[120:123], v[136:139], v[186:189], v[120:123]
	v_mfma_f32_16x16x32_bf16 v[112:115], v[128:131], v[194:197], v[112:115]
	v_mfma_f32_16x16x32_bf16 v[104:107], v[136:139], v[194:197], v[104:107]
	v_mfma_f32_16x16x32_bf16 v[100:103], v[128:131], v[206:209], v[100:103]
	v_mfma_f32_16x16x32_bf16 v[92:95], v[136:139], v[206:209], v[92:95]
	v_mfma_f32_16x16x32_bf16 v[84:87], v[128:131], v[214:217], v[84:87]
	v_mfma_f32_16x16x32_bf16 v[76:79], v[136:139], v[214:217], v[76:79]
	v_mfma_f32_16x16x32_bf16 v[124:127], v[132:135], v[190:193], v[124:127]
	v_mfma_f32_16x16x32_bf16 v[120:123], v[160:163], v[190:193], v[120:123]
	v_mfma_f32_16x16x32_bf16 v[112:115], v[132:135], v[202:205], v[112:115]
	v_mfma_f32_16x16x32_bf16 v[104:107], v[160:163], v[202:205], v[104:107]
	v_mfma_f32_16x16x32_bf16 v[100:103], v[132:135], v[210:213], v[100:103]
	v_mfma_f32_16x16x32_bf16 v[92:95], v[160:163], v[210:213], v[92:95]
	v_mfma_f32_16x16x32_bf16 v[84:87], v[132:135], v[218:221], v[84:87]
	v_mfma_f32_16x16x32_bf16 v[76:79], v[160:163], v[218:221], v[76:79]
	v_mfma_f32_16x16x32_bf16 v[116:119], v[164:167], v[186:189], v[116:119]
	v_mfma_f32_16x16x32_bf16 v[108:111], v[178:181], v[186:189], v[108:111]
	v_mfma_f32_16x16x32_bf16 v[96:99], v[164:167], v[194:197], v[96:99]
	v_mfma_f32_16x16x32_bf16 v[88:91], v[178:181], v[194:197], v[88:91]
	v_mfma_f32_16x16x32_bf16 v[80:83], v[164:167], v[206:209], v[80:83]
	v_mfma_f32_16x16x32_bf16 v[72:75], v[178:181], v[206:209], v[72:75]
	v_mfma_f32_16x16x32_bf16 v[68:71], v[164:167], v[214:217], v[68:71]
	v_mfma_f32_16x16x32_bf16 v[64:67], v[178:181], v[214:217], v[64:67]
	v_mfma_f32_16x16x32_bf16 v[116:119], v[174:177], v[190:193], v[116:119]
	v_mfma_f32_16x16x32_bf16 v[108:111], v[182:185], v[190:193], v[108:111]
	v_mfma_f32_16x16x32_bf16 v[96:99], v[174:177], v[202:205], v[96:99]
	v_mfma_f32_16x16x32_bf16 v[88:91], v[182:185], v[202:205], v[88:91]
	v_mfma_f32_16x16x32_bf16 v[80:83], v[174:177], v[210:213], v[80:83]
	v_mfma_f32_16x16x32_bf16 v[72:75], v[182:185], v[210:213], v[72:75]
	v_mfma_f32_16x16x32_bf16 v[68:71], v[174:177], v[218:221], v[68:71]
	v_mfma_f32_16x16x32_bf16 v[64:67], v[182:185], v[218:221], v[64:67]
	s_barrier
	s_add_i32 s56, s85, s3
	v_lshl_add_u64 v[198:199], v[198:199], 0, s[16:17]
	s_mov_b32 m0, s56
	ds_read_b128 v[186:189], v173 offset:49152
	ds_read_b128 v[190:193], v173 offset:50176
	ds_read_b128 v[194:197], v173 offset:51200
	ds_read_b128 v[202:205], v173 offset:52224
	ds_read_b128 v[206:209], v173 offset:53248
	ds_read_b128 v[210:213], v173 offset:54272
	ds_read_b128 v[214:217], v173 offset:55296
	ds_read_b128 v[218:221], v173 offset:56320
	global_load_lds_dwordx4 v[198:199], off
	s_add_i32 m0, s56, 0x2000
	s_add_u32 s52, s52, 0x40080
	v_lshl_add_u64 v[198:199], v[200:201], 0, s[16:17]
	s_addc_u32 s53, s53, 0
	s_add_i32 s56, s86, s3
	global_load_lds_dwordx4 v[198:199], off
	v_lshl_add_u64 v[198:199], s[52:53], 0, v[142:143]
	s_mov_b32 m0, s56
	s_nop 0
	global_load_lds_dwordx4 v[198:199], off
	v_lshl_add_u64 v[198:199], s[52:53], 0, v[146:147]
	s_add_i32 m0, s56, 0x2000
	s_nop 0
	global_load_lds_dwordx4 v[198:199], off
	v_lshl_add_u64 v[198:199], v[222:223], 0, s[16:17]
	s_mov_b32 m0, s69
	s_nop 0
	global_load_lds_dwordx4 v[198:199], off
	v_lshl_add_u64 v[198:199], v[224:225], 0, s[16:17]
	s_mov_b32 m0, s72
	s_nop 0
	global_load_lds_dwordx4 v[198:199], off
	s_waitcnt vmcnt(8)
	s_waitcnt lgkmcnt(0)
	s_barrier
	s_waitcnt lgkmcnt(0)
	v_mfma_f32_16x16x32_bf16 v[60:63], v[128:131], v[186:189], v[60:63]
	v_mfma_f32_16x16x32_bf16 v[56:59], v[136:139], v[186:189], v[56:59]
	v_mfma_f32_16x16x32_bf16 v[52:55], v[128:131], v[194:197], v[52:55]
	v_mfma_f32_16x16x32_bf16 v[44:47], v[136:139], v[194:197], v[44:47]
	v_mfma_f32_16x16x32_bf16 v[36:39], v[128:131], v[206:209], v[36:39]
	v_mfma_f32_16x16x32_bf16 v[28:31], v[136:139], v[206:209], v[28:31]
	v_mfma_f32_16x16x32_bf16 v[20:23], v[128:131], v[214:217], v[20:23]
	v_mfma_f32_16x16x32_bf16 v[12:15], v[136:139], v[214:217], v[12:15]
	v_mfma_f32_16x16x32_bf16 v[60:63], v[132:135], v[190:193], v[60:63]
	v_mfma_f32_16x16x32_bf16 v[56:59], v[160:163], v[190:193], v[56:59]
	v_mfma_f32_16x16x32_bf16 v[52:55], v[132:135], v[202:205], v[52:55]
	v_mfma_f32_16x16x32_bf16 v[44:47], v[160:163], v[202:205], v[44:47]
	v_mfma_f32_16x16x32_bf16 v[36:39], v[132:135], v[210:213], v[36:39]
	v_mfma_f32_16x16x32_bf16 v[28:31], v[160:163], v[210:213], v[28:31]
	v_mfma_f32_16x16x32_bf16 v[20:23], v[132:135], v[218:221], v[20:23]
	v_mfma_f32_16x16x32_bf16 v[12:15], v[160:163], v[218:221], v[12:15]
	v_mfma_f32_16x16x32_bf16 v[48:51], v[164:167], v[186:189], v[48:51]
	v_mfma_f32_16x16x32_bf16 v[40:43], v[178:181], v[186:189], v[40:43]
	v_mfma_f32_16x16x32_bf16 v[32:35], v[164:167], v[194:197], v[32:35]
	v_mfma_f32_16x16x32_bf16 v[24:27], v[178:181], v[194:197], v[24:27]
	v_mfma_f32_16x16x32_bf16 v[16:19], v[164:167], v[206:209], v[16:19]
	v_mfma_f32_16x16x32_bf16 v[8:11], v[178:181], v[206:209], v[8:11]
	v_mfma_f32_16x16x32_bf16 v[4:7], v[164:167], v[214:217], v[4:7]
	v_mfma_f32_16x16x32_bf16 v[0:3], v[178:181], v[214:217], v[0:3]
	v_mfma_f32_16x16x32_bf16 v[48:51], v[174:177], v[190:193], v[48:51]
	v_mfma_f32_16x16x32_bf16 v[40:43], v[182:185], v[190:193], v[40:43]
	v_mfma_f32_16x16x32_bf16 v[32:35], v[174:177], v[202:205], v[32:35]
	v_mfma_f32_16x16x32_bf16 v[24:27], v[182:185], v[202:205], v[24:27]
	v_mfma_f32_16x16x32_bf16 v[16:19], v[174:177], v[210:213], v[16:19]
	v_mfma_f32_16x16x32_bf16 v[8:11], v[182:185], v[210:213], v[8:11]
	v_mfma_f32_16x16x32_bf16 v[4:7], v[174:177], v[218:221], v[4:7]
	v_mfma_f32_16x16x32_bf16 v[0:3], v[182:185], v[218:221], v[0:3]
	s_barrier
	s_add_i32 s84, s84, 2
	s_add_u32 s44, s44, 0x100
	s_addc_u32 s45, s45, 0
	s_add_u32 s43, s43, 0x100
	s_addc_u32 s83, s83, 0
	s_cmp_gt_u32 s84, 13
	s_cbranch_scc0 .LBB0_177
	s_and_b64 vcc, exec, s[18:19]
	s_cbranch_vccz .LBB0_180
	s_barrier

.LBB0_359:
	s_or_b64 exec, exec, s[72:73]
	s_bfe_u32 s25, s11, 0x20003
	s_lshl_b32 s3, s25, 5
	s_or_b32 s1, s0, s3
	v_or_b32_e32 v2, s1, v116
	v_lshlrev_b32_e32 v8, 2, v2
	v_add_u32_e32 v0, s1, v79
	global_load_dword v10, v8, s[60:61]
	v_ashrrev_i32_e32 v1, 31, v0
	v_lshlrev_b64 v[0:1], 8, v[0:1]
	v_lshl_or_b32 v0, v78, 1, v0
	v_lshl_add_u64 v[2:3], s[42:43], 0, v[0:1]
	v_lshl_add_u64 v[4:5], s[44:45], 0, v[0:1]
	global_load_dwordx4 v[0:3], v[2:3], off
	s_nop 0
	global_load_dwordx4 v[4:7], v[4:5], off
	s_lshl_b32 s1, s11, 7
	s_and_b32 s18, s1, 0xfffff000
	s_ashr_i32 s19, s18, 31
	s_lshl_b64 s[22:23], s[18:19], 11
	s_add_u32 s1, s57, s22
	s_addc_u32 s16, s63, s23
	s_lshl_b32 s0, s0, 1
	s_add_u32 s20, s1, s0
	s_addc_u32 s21, s16, 0
	global_load_dword v12, v8, s[54:55]
	global_load_dword v13, v8, s[58:59]
	v_lshl_add_u64 v[8:9], s[20:21], 0, v[82:83]
	v_lshl_add_u64 v[20:21], s[20:21], 0, v[84:85]
	v_lshl_add_u64 v[24:25], s[20:21], 0, v[86:87]
	v_lshl_add_u64 v[28:29], s[20:21], 0, v[88:89]
	v_lshl_add_u64 v[32:33], s[20:21], 0, v[90:91]
	v_lshl_add_u64 v[34:35], s[20:21], 0, v[92:93]
	v_lshl_add_u64 v[36:37], s[20:21], 0, v[94:95]
	v_lshl_add_u64 v[38:39], s[20:21], 0, v[96:97]
	v_lshl_add_u64 v[40:41], s[20:21], 0, v[98:99]
	v_lshl_add_u64 v[42:43], s[20:21], 0, v[100:101]
	global_load_dwordx4 v[16:19], v[8:9], off
	s_nop 0
	global_load_dwordx4 v[20:23], v[20:21], off
	s_nop 0
	global_load_dwordx4 v[24:27], v[24:25], off
	s_nop 0
	global_load_dwordx4 v[28:31], v[28:29], off
	s_nop 0
	global_load_dwordx4 v[48:51], v[32:33], off
	global_load_dwordx4 v[52:55], v[34:35], off
	global_load_dwordx4 v[56:59], v[36:37], off
	global_load_dwordx4 v[60:63], v[38:39], off
	global_load_dwordx4 v[64:67], v[40:41], off
	global_load_dwordx4 v[68:71], v[42:43], off
	v_lshl_add_u64 v[44:45], s[20:21], 0, v[102:103]
	v_add_u32_e32 v14, 0x22a00, v124
	v_add_u32_e32 v15, 0x24a00, v124
	s_add_u32 s1, s65, s22
	s_mov_b32 s24, 0
	s_waitcnt vmcnt(14)
	v_mul_f32_e32 v8, 0xbfb8aa3b, v10
	v_exp_f32_e32 v36, v8
	global_load_dwordx4 v[8:11], v[44:45], off
	s_waitcnt vmcnt(14)
	ds_write_b128 v14, v[0:3]
	s_waitcnt vmcnt(13)
	ds_write_b128 v15, v[4:7]
	v_add_f32_e32 v2, 1.0, v36
	v_add_f32_e32 v3, -1.0, v2
	v_frexp_mant_f32_e32 v4, v2
	v_cvt_f64_f32_e32 v[0:1], v2
	v_sub_f32_e32 v5, v3, v2
	v_frexp_exp_i32_f64_e32 v0, v[0:1]
	v_cmp_gt_f32_e64 s[16:17], s94, v4
	v_sub_f32_e32 v3, v36, v3
	v_add_f32_e32 v1, 1.0, v5
	v_subbrev_co_u32_e64 v0, s[16:17], 0, v0, s[16:17]
	v_add_f32_e32 v1, v3, v1
	v_sub_u32_e32 v3, 0, v0
	v_ldexp_f32 v2, v2, v3
	v_add_f32_e32 v4, -1.0, v2
	v_add_f32_e32 v5, 1.0, v2
	v_ldexp_f32 v1, v1, v3
	v_add_f32_e32 v3, 1.0, v4
	v_add_f32_e32 v6, -1.0, v5
	v_sub_f32_e32 v3, v2, v3
	v_sub_f32_e32 v2, v2, v6
	v_add_f32_e32 v6, v1, v3
	v_add_f32_e32 v1, v1, v2
	v_add_f32_e32 v14, v5, v1
	v_rcp_f32_e32 v15, v14
	v_add_f32_e32 v3, v4, v6
	v_sub_f32_e32 v4, v3, v4
	v_sub_f32_e32 v2, v14, v5
	v_mul_f32_e32 v33, v3, v15
	v_sub_f32_e32 v32, v6, v4
	v_mul_f32_e32 v4, v14, v33
	v_sub_f32_e32 v1, v1, v2
	v_fma_f32 v6, v33, v14, -v4
	v_fmac_f32_e32 v6, v33, v1
	v_add_f32_e32 v2, v4, v6
	v_sub_f32_e32 v5, v3, v2
	v_mov_b32_e32 v7, v2
	v_pk_add_f32 v[2:3], v[2:3], v[4:5] neg_lo:[0,1] neg_hi:[0,1]
	v_cvt_f32_i32_e32 v0, v0
	v_pk_add_f32 v[2:3], v[2:3], v[6:7] neg_lo:[0,1] neg_hi:[0,1]
	v_cmp_neq_f32_e64 s[16:17], s96, v36
	v_add_f32_e32 v3, v32, v3
	v_add_f32_e32 v2, v2, v3
	v_add_f32_e32 v3, v5, v2
	v_mul_f32_e32 v7, v15, v3
	v_mul_f32_e32 v4, v14, v7
	v_sub_f32_e32 v5, v5, v3
	v_add_f32_e32 v34, v33, v7
	v_fma_f32 v6, v7, v14, -v4
	v_add_f32_e32 v32, v2, v5
	v_sub_f32_e32 v2, v34, v33
	v_fmac_f32_e32 v6, v7, v1
	v_sub_f32_e32 v1, v7, v2
	v_add_f32_e32 v2, v4, v6
	v_sub_f32_e32 v5, v3, v2
	v_mov_b32_e32 v7, v2
	v_pk_add_f32 v[2:3], v[2:3], v[4:5] neg_lo:[0,1] neg_hi:[0,1]
	s_waitcnt vmcnt(12)
	v_mul_f32_e32 v108, 0xbfb8aa3b, v12
	v_pk_add_f32 v[2:3], v[2:3], v[6:7] neg_lo:[0,1] neg_hi:[0,1]
	s_waitcnt vmcnt(11)
	v_mul_f32_e32 v110, 0xbfb8aa3b, v13
	v_add_f32_e32 v3, v32, v3
	v_add_f32_e32 v2, v2, v3
	v_add_f32_e32 v2, v5, v2
	v_mul_f32_e32 v2, v15, v2
	v_add_f32_e32 v1, v1, v2
	v_add_f32_e32 v2, v34, v1
	v_mul_f32_e32 v4, v2, v2
	v_sub_f32_e32 v5, v2, v34
	v_fmamk_f32 v6, v4, 0x3e9b6dac, v125
	v_sub_f32_e32 v5, v1, v5
	v_mul_f32_e32 v1, v2, v4
	v_fmaak_f32 v105, v4, v6, 0x3f2aaada
	v_ldexp_f32 v7, v5, 1
	v_pk_mul_f32 v[4:5], v[0:1], v[104:105]
	v_ldexp_f32 v3, v2, 1
	v_fma_f32 v2, v0, s95, -v4
	v_fmac_f32_e32 v2, 0xb102e308, v0
	v_pk_add_f32 v[0:1], v[4:5], v[2:3]
	v_mov_b32_e32 v6, v4
	v_sub_f32_e32 v32, v1, v3
	v_pk_add_f32 v[14:15], v[0:1], v[4:5] neg_lo:[0,1] neg_hi:[0,1]
	v_sub_f32_e32 v4, v5, v32
	v_add_f32_e32 v7, v7, v4
	v_pk_add_f32 v[4:5], v[0:1], v[6:7]
	v_mov_b32_e32 v3, v0
	v_mov_b32_e32 v15, v5
	v_pk_add_f32 v[34:35], v[2:3], v[14:15] neg_lo:[0,1] neg_hi:[0,1]
	v_pk_add_f32 v[2:3], v[2:3], v[14:15]
	v_mov_b32_e32 v32, v5
	v_pk_add_f32 v[14:15], v[2:3], v[0:1] op_sel:[1,0] op_sel_hi:[0,1] neg_lo:[0,1] neg_hi:[0,1]
	v_mov_b32_e32 v33, v3
	v_pk_add_f32 v[4:5], v[4:5], v[14:15] op_sel_hi:[1,0] neg_lo:[0,1] neg_hi:[0,1]
	v_pk_mov_b32 v[14:15], v[0:1], v[14:15] op_sel:[1,0]
	v_mov_b32_e32 v6, v7
	v_pk_add_f32 v[14:15], v[32:33], v[14:15] neg_lo:[0,1] neg_hi:[0,1]
	v_mov_b32_e32 v7, v0
	v_pk_add_f32 v[0:1], v[6:7], v[14:15] neg_lo:[0,1] neg_hi:[0,1]
	v_mov_b32_e32 v4, v34
	v_pk_add_f32 v[4:5], v[4:5], v[0:1]
	v_mov_b32_e32 v35, v3
	v_pk_add_f32 v[6:7], v[4:5], v[4:5] op_sel:[0,1] op_sel_hi:[1,0]
	s_waitcnt vmcnt(10)
	v_cndmask_b32_e64 v33, v17, 0, s[4:5]
	v_pk_add_f32 v[2:3], v[2:3], v[6:7] op_sel:[1,0] op_sel_hi:[0,1]
	v_mov_b32_e32 v5, v2
	v_pk_add_f32 v[14:15], v[4:5], v[34:35] neg_lo:[0,1] neg_hi:[0,1]
	v_mov_b32_e32 v1, v6
	v_sub_f32_e32 v3, v4, v14
	v_pk_add_f32 v[0:1], v[0:1], v[14:15] neg_lo:[0,1] neg_hi:[0,1]
	v_sub_f32_e32 v3, v34, v3
	v_add_f32_e32 v0, v0, v3
	v_add_f32_e32 v0, v0, v1
	v_add_f32_e32 v0, v2, v0
	v_cndmask_b32_e64 v0, v127, v0, s[16:17]
	v_cmp_ngt_f32_e64 s[16:17], -1.0, v36
	v_cndmask_b32_e64 v35, v19, 0, s[4:5]
	v_cndmask_b32_e64 v34, v18, 0, s[4:5]
	v_cndmask_b32_e64 v0, v128, v0, s[16:17]
	v_cmp_neq_f32_e64 s[16:17], -1.0, v36
	v_cndmask_b32_e64 v32, v16, 0, s[4:5]
	s_waitcnt vmcnt(9)
	v_cndmask_b32_e64 v39, v23, 0, s[4:5]
	v_cndmask_b32_e64 v0, v129, v0, s[16:17]
	v_cmp_lt_f32_e64 s[16:17], |v36|, s97
	v_cndmask_b32_e64 v38, v22, 0, s[4:5]
	v_cndmask_b32_e64 v37, v21, 0, s[4:5]
	v_cndmask_b32_e64 v0, v0, v36, s[16:17]
	s_addc_u32 s16, s67, s23
	s_add_u32 s0, s1, s0
	s_addc_u32 s1, s16, 0
	s_lshl_b32 s16, s25, 6
	s_add_u32 s22, s0, s16
	s_addc_u32 s23, s1, 0
	s_lshl_b64 s[0:1], s[18:19], 2
	s_add_u32 s0, s30, s0
	s_addc_u32 s1, s31, s1
	s_lshl_b32 s16, s52, 19
	s_lshl_b32 s17, s25, 17
	v_mul_f32_e32 v0, 0x41000000, v0
	s_or_b32 s16, s17, s16
	v_mul_f32_e32 v106, 0xbfb8aa3b, v0
	v_mul_f32_e32 v112, -2.0, v0
	s_add_u32 s25, s0, s16
	v_cndmask_b32_e64 v36, v20, 0, s[4:5]
	s_waitcnt vmcnt(8)
	v_cndmask_b32_e64 v43, v27, 0, s[4:5]
	v_cndmask_b32_e64 v42, v26, 0, s[4:5]
	v_cndmask_b32_e64 v41, v25, 0, s[4:5]
	v_cndmask_b32_e64 v40, v24, 0, s[4:5]
	s_waitcnt vmcnt(7)
	v_cndmask_b32_e64 v47, v31, 0, s[6:7]
	v_cndmask_b32_e64 v46, v30, 0, s[6:7]
	v_cndmask_b32_e64 v45, v29, 0, s[6:7]
	v_cndmask_b32_e64 v44, v28, 0, s[6:7]
	s_waitcnt vmcnt(6)
	v_cndmask_b32_e64 v51, v51, 0, s[6:7]
	v_cndmask_b32_e64 v50, v50, 0, s[6:7]
	v_cndmask_b32_e64 v49, v49, 0, s[6:7]
	v_cndmask_b32_e64 v48, v48, 0, s[6:7]
	s_waitcnt vmcnt(5)
	v_cndmask_b32_e64 v55, v55, 0, s[6:7]
	v_cndmask_b32_e64 v54, v54, 0, s[6:7]
	v_cndmask_b32_e64 v53, v53, 0, s[6:7]
	v_cndmask_b32_e64 v52, v52, 0, s[6:7]
	s_waitcnt vmcnt(4)
	v_cndmask_b32_e64 v59, v59, 0, s[6:7]
	v_cndmask_b32_e64 v58, v58, 0, s[6:7]
	v_cndmask_b32_e64 v57, v57, 0, s[6:7]
	v_cndmask_b32_e64 v56, v56, 0, s[6:7]
	s_waitcnt vmcnt(3)
	v_cndmask_b32_e64 v63, v63, 0, s[6:7]
	v_cndmask_b32_e64 v62, v62, 0, s[6:7]
	v_cndmask_b32_e64 v61, v61, 0, s[6:7]
	v_cndmask_b32_e64 v60, v60, 0, s[6:7]
	s_waitcnt vmcnt(2)
	v_cndmask_b32_e64 v67, v67, 0, s[6:7]
	v_cndmask_b32_e64 v66, v66, 0, s[6:7]
	v_cndmask_b32_e64 v65, v65, 0, s[6:7]
	v_cndmask_b32_e64 v64, v64, 0, s[6:7]
	s_waitcnt vmcnt(1)
	v_cndmask_b32_e64 v71, v71, 0, s[6:7]
	v_cndmask_b32_e64 v70, v70, 0, s[6:7]
	v_cndmask_b32_e64 v69, v69, 0, s[6:7]
	v_cndmask_b32_e64 v68, v68, 0, s[6:7]
	s_waitcnt vmcnt(0)
	v_cndmask_b32_e64 v75, v11, 0, s[6:7]
	v_cndmask_b32_e64 v74, v10, 0, s[6:7]
	v_cndmask_b32_e64 v73, v9, 0, s[6:7]
	v_cndmask_b32_e64 v72, v8, 0, s[6:7]
	v_mov_b32_e32 v109, v108
	v_mov_b32_e32 v111, v110
	v_mov_b32_e32 v107, v106
	v_mov_b32_e32 v113, v112
	s_addc_u32 s26, s1, 0
	v_mov_b32_e32 v105, 0
	s_waitcnt lgkmcnt(0)
	v_bfe_u32 v234, v76, 5, 1
	v_bfe_u32 v235, v116, 3, 1
	v_and_b32_e32 v236, 1, v116
	v_lshlrev_b32_e32 v236, 4, v236
	v_mov_b32_e32 v237, 0x3c00
	v_cmp_eq_u32_e32 vcc, v234, v235
	v_lshlrev_b32_e32 v237, v236, v237
	s_nop 1
	v_cndmask_b32_e32 v237, 0, v237, vcc
	v_bfe_u32 v238, v116, 1, 2
	v_cmp_gt_u32_e64 s[16:17], 16, v116
	v_cmp_eq_u32_e32 vcc, 0, v238
	s_nop 1
	v_cndmask_b32_e32 v239, 0, v237, vcc
	s_nop 0
	v_cndmask_b32_e64 v168, 0, v239, s[16:17]
	v_cndmask_b32_e64 v172, v239, 0, s[16:17]
	v_cmp_eq_u32_e32 vcc, 1, v238
	s_nop 1
	v_cndmask_b32_e32 v239, 0, v237, vcc
	s_nop 0
	v_cndmask_b32_e64 v169, 0, v239, s[16:17]
	v_cndmask_b32_e64 v173, v239, 0, s[16:17]
	v_cmp_eq_u32_e32 vcc, 2, v238
	s_nop 1
	v_cndmask_b32_e32 v239, 0, v237, vcc
	s_nop 0
	v_cndmask_b32_e64 v170, 0, v239, s[16:17]
	v_cndmask_b32_e64 v174, v239, 0, s[16:17]
	v_cmp_eq_u32_e32 vcc, 3, v238
	s_nop 1
	v_cndmask_b32_e32 v239, 0, v237, vcc
	s_nop 0
	v_cndmask_b32_e64 v171, 0, v239, s[16:17]
	v_cndmask_b32_e64 v175, v239, 0, s[16:17]
	v_bfe_u32 v80, v76, 5, 1
	v_lshlrev_b32_e32 v132, 4, v76
	v_and_b32_e32 v132, 0x70, v132
	v_lshlrev_b32_e32 v80, 4, v80
	v_lshlrev_b32_e32 v133, 8, v116
	v_or_b32_e32 v134, 0, v80
	v_xor_b32_e32 v134, v134, v132
	v_add_u32_e32 v134, v133, v134
	v_add_u32_e32 v234, s90, v134
	v_add_u32_e32 v238, 0x22a00, v134
	v_or_b32_e32 v134, 32, v80
	v_xor_b32_e32 v134, v134, v132
	v_add_u32_e32 v134, v133, v134
	v_add_u32_e32 v235, s90, v134
	v_add_u32_e32 v239, 0x22a00, v134
	v_or_b32_e32 v134, 64, v80
	v_xor_b32_e32 v134, v134, v132
	v_add_u32_e32 v134, v133, v134
	v_add_u32_e32 v236, s90, v134
	v_add_u32_e32 v151, 0x22a00, v134
	v_or_b32_e32 v134, 96, v80
	v_xor_b32_e32 v134, v134, v132
	v_add_u32_e32 v134, v133, v134
	v_add_u32_e32 v237, s90, v134
	v_add_u32_e32 v176, 0x22a00, v134
	s_barrier
	s_branch .LBB0_361

.LBB0_363:
	v_bfe_u32 v80, v115, 5, 1
	v_and_b32_e32 v133, 31, v115
	v_lshlrev_b32_e32 v132, 8, v133
	v_lshlrev_b32_e32 v146, 4, v80
	v_lshlrev_b32_e32 v0, 4, v115
	v_and_b32_e32 v147, 0x70, v0
	v_add_u32_e32 v148, s90, v132
	v_lshlrev_b32_e32 v80, 7, v80
	v_or3_b32 v80, v80, s91, v133
	v_lshlrev_b32_e32 v80, 2, v80
	v_and_b32_e32 v132, 1, v115
	s_lshl_b32 s0, s24, 19
	s_waitcnt lgkmcnt(0)
	ds_read_b128 v[178:181], v234
	ds_read_b128 v[182:185], v238
	ds_read_b128 v[186:189], v238 offset:8192
	ds_read_b128 v[190:193], v235
	ds_read_b128 v[194:197], v239
	ds_read_b128 v[198:201], v239 offset:8192
	ds_read_b128 v[202:205], v236
	ds_read_b128 v[206:209], v151
	ds_read_b128 v[210:213], v151 offset:8192
	ds_read_b128 v[214:217], v237
	ds_read_b128 v[218:221], v176
	ds_read_b128 v[222:225], v176 offset:8192
	s_waitcnt lgkmcnt(11)
	s_waitcnt lgkmcnt(10)
	v_mfma_f32_32x32x16_f16 v[0:15], v[178:181], v[182:185], 0
	s_waitcnt lgkmcnt(9)
	v_mfma_f32_32x32x16_f16 v[16:31], v[178:181], v[186:189], 0
	ds_read_b128 v[226:229], v234 offset:128
	ds_read_b128 v[230:233], v238 offset:128
	ds_read_b128 v[134:137], v238 offset:8320
	s_waitcnt lgkmcnt(11)
	s_waitcnt lgkmcnt(10)
	v_mfma_f32_32x32x16_f16 v[0:15], v[190:193], v[194:197], v[0:15]
	s_waitcnt lgkmcnt(9)
	v_mfma_f32_32x32x16_f16 v[16:31], v[190:193], v[198:201], v[16:31]
	ds_read_b128 v[138:141], v235 offset:128
	ds_read_b128 v[142:145], v239 offset:128
	ds_read_b128 v[178:181], v239 offset:8320
	s_waitcnt lgkmcnt(11)
	s_waitcnt lgkmcnt(10)
	v_mfma_f32_32x32x16_f16 v[0:15], v[202:205], v[206:209], v[0:15]
	s_waitcnt lgkmcnt(9)
	v_mfma_f32_32x32x16_f16 v[16:31], v[202:205], v[210:213], v[16:31]
	ds_read_b128 v[182:185], v236 offset:128
	ds_read_b128 v[186:189], v151 offset:128
	ds_read_b128 v[190:193], v151 offset:8320
	s_waitcnt lgkmcnt(11)
	s_waitcnt lgkmcnt(10)
	v_mfma_f32_32x32x16_f16 v[0:15], v[214:217], v[218:221], v[0:15]
	s_waitcnt lgkmcnt(9)
	v_mfma_f32_32x32x16_f16 v[16:31], v[214:217], v[222:225], v[16:31]
	ds_read_b128 v[194:197], v237 offset:128
	ds_read_b128 v[198:201], v176 offset:128
	ds_read_b128 v[202:205], v176 offset:8320
	s_waitcnt lgkmcnt(11)
	s_waitcnt lgkmcnt(10)
	v_mfma_f32_32x32x16_f16 v[0:15], v[226:229], v[230:233], v[0:15]
	s_waitcnt lgkmcnt(9)
	v_mfma_f32_32x32x16_f16 v[16:31], v[226:229], v[134:137], v[16:31]
	s_waitcnt lgkmcnt(8)
	s_waitcnt lgkmcnt(7)
	v_mfma_f32_32x32x16_f16 v[0:15], v[138:141], v[142:145], v[0:15]
	s_waitcnt lgkmcnt(6)
	v_mfma_f32_32x32x16_f16 v[16:31], v[138:141], v[178:181], v[16:31]
	s_waitcnt lgkmcnt(5)
	s_waitcnt lgkmcnt(4)
	v_mfma_f32_32x32x16_f16 v[0:15], v[182:185], v[186:189], v[0:15]
	s_waitcnt lgkmcnt(3)
	v_mfma_f32_32x32x16_f16 v[16:31], v[182:185], v[190:193], v[16:31]
	s_waitcnt lgkmcnt(2)
	s_waitcnt lgkmcnt(1)
	v_mfma_f32_32x32x16_f16 v[0:15], v[194:197], v[198:201], v[0:15]
	s_waitcnt lgkmcnt(0)
	v_mfma_f32_32x32x16_f16 v[16:31], v[194:197], v[202:205], v[16:31]
	s_lshl_b32 s18, s3, 1
	s_add_i32 s19, s18, 32
	v_bitop3_b32 v134, v146, v147, s18 bitop3:0x36
	v_add_u32_e32 v134, v148, v134
	ds_read_b128 v[134:137], v134
	v_bitop3_b32 v138, v146, v147, s19 bitop3:0x36
	v_add_u32_e32 v138, v148, v138
	ds_read_b128 v[138:141], v138
	v_add_u32_e32 v250, s33, v80
	s_waitcnt lgkmcnt(1)
	v_mfma_f32_32x32x16_f16 v[152:167], v[134:137], v[168:171], 0
	s_waitcnt lgkmcnt(0)
	v_mfma_f32_32x32x16_f16 v[152:167], v[138:141], v[172:175], v[152:167]
	v_lshl_or_b32 v251, v132, 5, s0
	v_lshl_add_u32 v80, v114, 11, v251
	global_load_dwordx4 v[240:243], v80, s[22:23] offset:16
	global_load_dwordx4 v[244:247], v80, s[22:23]
	v_lshl_add_u64 v[248:249], s[22:23], 0, v[80:81]
	s_nop 4
	v_pk_fma_f32 v[0:1], v[0:1], s[56:57], v[108:109] op_sel_hi:[1,0,1] neg_lo:[1,0,0] neg_hi:[1,0,0]
	v_pk_fma_f32 v[4:5], v[4:5], s[56:57], v[108:109] op_sel_hi:[1,0,1] neg_lo:[1,0,0] neg_hi:[1,0,0]
	v_pk_fma_f32 v[8:9], v[8:9], s[56:57], v[108:109] op_sel_hi:[1,0,1] neg_lo:[1,0,0] neg_hi:[1,0,0]
	v_pk_fma_f32 v[12:13], v[12:13], s[56:57], v[108:109] op_sel_hi:[1,0,1] neg_lo:[1,0,0] neg_hi:[1,0,0]
	v_pk_fma_f32 v[16:17], v[16:17], s[56:57], v[110:111] op_sel_hi:[1,0,1] neg_lo:[1,0,0] neg_hi:[1,0,0]
	v_pk_fma_f32 v[20:21], v[20:21], s[56:57], v[110:111] op_sel_hi:[1,0,1] neg_lo:[1,0,0] neg_hi:[1,0,0]
	v_pk_fma_f32 v[24:25], v[24:25], s[56:57], v[110:111] op_sel_hi:[1,0,1] neg_lo:[1,0,0] neg_hi:[1,0,0]
	v_pk_fma_f32 v[28:29], v[28:29], s[56:57], v[110:111] op_sel_hi:[1,0,1] neg_lo:[1,0,0] neg_hi:[1,0,0]
	v_pk_fma_f32 v[18:19], v[18:19], s[56:57], v[110:111] op_sel_hi:[1,0,1] neg_lo:[1,0,0] neg_hi:[1,0,0]
	v_pk_fma_f32 v[22:23], v[22:23], s[56:57], v[110:111] op_sel_hi:[1,0,1] neg_lo:[1,0,0] neg_hi:[1,0,0]
	v_pk_fma_f32 v[26:27], v[26:27], s[56:57], v[110:111] op_sel_hi:[1,0,1] neg_lo:[1,0,0] neg_hi:[1,0,0]
	v_pk_fma_f32 v[30:31], v[30:31], s[56:57], v[110:111] op_sel_hi:[1,0,1] neg_lo:[1,0,0] neg_hi:[1,0,0]
	v_min_f32_e32 v191, 0x42700000, v0
	v_min_f32_e32 v205, 0x42700000, v4
	v_min_f32_e32 v219, 0x42700000, v8
	v_min_f32_e32 v233, 0x42700000, v12
	v_min_f32_e32 v1, 0x42700000, v1
	v_min_f32_e32 v5, 0x42700000, v5
	v_min_f32_e32 v9, 0x42700000, v9
	v_min_f32_e32 v13, 0x42700000, v13
	v_min_f32_e32 v181, 0x42700000, v16
	v_min_f32_e32 v195, 0x42700000, v20
	v_min_f32_e32 v209, 0x42700000, v24
	v_min_f32_e32 v223, 0x42700000, v28
	v_min_f32_e32 v182, 0x42700000, v17
	v_min_f32_e32 v196, 0x42700000, v21
	v_min_f32_e32 v210, 0x42700000, v25
	v_min_f32_e32 v224, 0x42700000, v29
	v_min_f32_e32 v190, 0x42700000, v18
	v_min_f32_e32 v204, 0x42700000, v22
	v_min_f32_e32 v218, 0x42700000, v26
	v_min_f32_e32 v232, 0x42700000, v30
	v_min_f32_e32 v183, 0x42700000, v19
	v_min_f32_e32 v197, 0x42700000, v23
	v_min_f32_e32 v211, 0x42700000, v27
	v_min_f32_e32 v225, 0x42700000, v31
	v_exp_f32_e32 v16, v191
	v_exp_f32_e32 v20, v205
	v_exp_f32_e32 v24, v219
	v_exp_f32_e32 v28, v233
	v_exp_f32_e32 v17, v1
	v_exp_f32_e32 v21, v5
	v_exp_f32_e32 v25, v9
	v_exp_f32_e32 v29, v13
	v_exp_f32_e32 v18, v181
	v_exp_f32_e32 v22, v195
	v_exp_f32_e32 v26, v209
	v_exp_f32_e32 v30, v223
	v_exp_f32_e32 v19, v182
	v_exp_f32_e32 v23, v196
	v_exp_f32_e32 v27, v210
	v_exp_f32_e32 v31, v224
	v_pk_fma_f32 v[2:3], v[2:3], s[56:57], v[108:109] op_sel_hi:[1,0,1] neg_lo:[1,0,0] neg_hi:[1,0,0]
	v_pk_fma_f32 v[6:7], v[6:7], s[56:57], v[108:109] op_sel_hi:[1,0,1] neg_lo:[1,0,0] neg_hi:[1,0,0]
	v_pk_fma_f32 v[10:11], v[10:11], s[56:57], v[108:109] op_sel_hi:[1,0,1] neg_lo:[1,0,0] neg_hi:[1,0,0]
	v_pk_fma_f32 v[14:15], v[14:15], s[56:57], v[108:109] op_sel_hi:[1,0,1] neg_lo:[1,0,0] neg_hi:[1,0,0]
	v_exp_f32_e32 v180, v190
	v_exp_f32_e32 v194, v204
	v_exp_f32_e32 v208, v218
	v_exp_f32_e32 v222, v232
	v_min_f32_e32 v190, 0x42700000, v2
	v_min_f32_e32 v204, 0x42700000, v6
	v_min_f32_e32 v218, 0x42700000, v10
	v_min_f32_e32 v232, 0x42700000, v14
	v_min_f32_e32 v191, 0x42700000, v3
	v_min_f32_e32 v205, 0x42700000, v7
	v_min_f32_e32 v219, 0x42700000, v11
	v_min_f32_e32 v233, 0x42700000, v15
	v_exp_f32_e32 v181, v183
	v_exp_f32_e32 v195, v197
	v_exp_f32_e32 v209, v211
	v_exp_f32_e32 v223, v225
	v_exp_f32_e32 v2, v190
	v_exp_f32_e32 v6, v204
	v_exp_f32_e32 v10, v218
	v_exp_f32_e32 v14, v232
	v_exp_f32_e32 v3, v191
	v_exp_f32_e32 v7, v205
	v_exp_f32_e32 v11, v219
	v_exp_f32_e32 v15, v233
	v_pk_add_f32 v[16:17], v[16:17], 1.0 op_sel_hi:[1,0]
	v_pk_add_f32 v[20:21], v[20:21], 1.0 op_sel_hi:[1,0]
	v_pk_add_f32 v[24:25], v[24:25], 1.0 op_sel_hi:[1,0]
	v_pk_add_f32 v[28:29], v[28:29], 1.0 op_sel_hi:[1,0]
	v_pk_add_f32 v[18:19], v[18:19], 1.0 op_sel_hi:[1,0]
	v_pk_add_f32 v[22:23], v[22:23], 1.0 op_sel_hi:[1,0]
	v_pk_add_f32 v[26:27], v[26:27], 1.0 op_sel_hi:[1,0]
	v_pk_add_f32 v[30:31], v[30:31], 1.0 op_sel_hi:[1,0]
	v_pk_add_f32 v[180:181], v[180:181], 1.0 op_sel_hi:[1,0]
	v_pk_add_f32 v[194:195], v[194:195], 1.0 op_sel_hi:[1,0]
	v_pk_add_f32 v[208:209], v[208:209], 1.0 op_sel_hi:[1,0]
	v_pk_add_f32 v[222:223], v[222:223], 1.0 op_sel_hi:[1,0]
	v_pk_mul_f32 v[182:183], v[16:17], v[18:19]
	v_pk_mul_f32 v[196:197], v[20:21], v[22:23]
	v_pk_mul_f32 v[210:211], v[24:25], v[26:27]
	v_pk_mul_f32 v[224:225], v[28:29], v[30:31]
	v_pk_add_f32 v[2:3], v[2:3], 1.0 op_sel_hi:[1,0]
	v_pk_add_f32 v[6:7], v[6:7], 1.0 op_sel_hi:[1,0]
	v_pk_add_f32 v[10:11], v[10:11], 1.0 op_sel_hi:[1,0]
	v_pk_add_f32 v[14:15], v[14:15], 1.0 op_sel_hi:[1,0]
	v_rcp_f32_e32 v182, v182
	v_rcp_f32_e32 v196, v196
	v_rcp_f32_e32 v210, v210
	v_rcp_f32_e32 v224, v224
	v_rcp_f32_e32 v183, v183
	v_rcp_f32_e32 v197, v197
	v_rcp_f32_e32 v211, v211
	v_rcp_f32_e32 v225, v225
	v_pk_mul_f32 v[184:185], v[2:3], v[180:181]
	v_pk_mul_f32 v[198:199], v[6:7], v[194:195]
	v_pk_mul_f32 v[212:213], v[10:11], v[208:209]
	v_pk_mul_f32 v[226:227], v[14:15], v[222:223]
	v_mov_b64_e32 v[178:179], s[64:65]
	v_mov_b64_e32 v[192:193], s[64:65]
	v_mov_b64_e32 v[206:207], s[64:65]
	v_mov_b64_e32 v[220:221], s[64:65]
	v_rcp_f32_e32 v184, v184
	v_rcp_f32_e32 v198, v198
	v_rcp_f32_e32 v212, v212
	v_rcp_f32_e32 v226, v226
	v_rcp_f32_e32 v185, v185
	v_rcp_f32_e32 v199, v199
	v_rcp_f32_e32 v213, v213
	v_rcp_f32_e32 v227, v227
	v_pk_mul_f32 v[18:19], v[18:19], v[182:183]
	v_pk_mul_f32 v[22:23], v[22:23], v[196:197]
	v_pk_mul_f32 v[26:27], v[26:27], v[210:211]
	v_pk_mul_f32 v[30:31], v[30:31], v[224:225]
	v_pk_mul_f32 v[16:17], v[16:17], v[182:183]
	v_pk_mul_f32 v[20:21], v[20:21], v[196:197]
	v_pk_mul_f32 v[24:25], v[24:25], v[210:211]
	v_pk_mul_f32 v[28:29], v[28:29], v[224:225]
	v_pk_mul_f32 v[182:183], v[106:107], v[18:19]
	v_pk_mul_f32 v[196:197], v[106:107], v[22:23]
	v_pk_mul_f32 v[210:211], v[106:107], v[26:27]
	v_pk_mul_f32 v[224:225], v[106:107], v[30:31]
	v_pk_mul_f32 v[18:19], v[112:113], v[18:19]
	v_pk_mul_f32 v[22:23], v[112:113], v[22:23]
	v_pk_mul_f32 v[26:27], v[112:113], v[26:27]
	v_pk_mul_f32 v[30:31], v[112:113], v[30:31]
	v_exp_f32_e32 v182, v182
	v_exp_f32_e32 v196, v196
	v_exp_f32_e32 v210, v210
	v_exp_f32_e32 v224, v224
	v_pk_fma_f32 v[186:187], v[18:19], s[62:63], v[178:179] op_sel_hi:[1,0,0]
	v_pk_fma_f32 v[200:201], v[22:23], s[62:63], v[192:193] op_sel_hi:[1,0,0]
	v_pk_fma_f32 v[214:215], v[26:27], s[62:63], v[206:207] op_sel_hi:[1,0,0]
	v_pk_fma_f32 v[228:229], v[30:31], s[62:63], v[220:221] op_sel_hi:[1,0,0]
	v_exp_f32_e32 v183, v183
	v_exp_f32_e32 v197, v197
	v_exp_f32_e32 v211, v211
	v_exp_f32_e32 v225, v225
	v_pk_mul_f32 v[180:181], v[180:181], v[184:185]
	v_pk_mul_f32 v[194:195], v[194:195], v[198:199]
	v_pk_mul_f32 v[208:209], v[208:209], v[212:213]
	v_pk_mul_f32 v[222:223], v[222:223], v[226:227]
	v_pk_mul_f32 v[2:3], v[2:3], v[184:185]
	v_pk_mul_f32 v[6:7], v[6:7], v[198:199]
	v_pk_mul_f32 v[10:11], v[10:11], v[212:213]
	v_pk_mul_f32 v[14:15], v[14:15], v[226:227]
	v_pk_fma_f32 v[184:185], v[18:19], v[186:187], s[66:67] op_sel_hi:[1,1,0]
	v_pk_fma_f32 v[198:199], v[22:23], v[200:201], s[66:67] op_sel_hi:[1,1,0]
	v_pk_fma_f32 v[212:213], v[26:27], v[214:215], s[66:67] op_sel_hi:[1,1,0]
	v_pk_fma_f32 v[226:227], v[30:31], v[228:229], s[66:67] op_sel_hi:[1,1,0]
	v_pk_mul_f32 v[186:187], v[106:107], v[180:181]
	v_pk_mul_f32 v[200:201], v[106:107], v[194:195]
	v_pk_mul_f32 v[214:215], v[106:107], v[208:209]
	v_pk_mul_f32 v[228:229], v[106:107], v[222:223]
	v_pk_fma_f32 v[184:185], v[18:19], v[184:185], s[68:69] op_sel_hi:[1,1,0]
	v_pk_fma_f32 v[198:199], v[22:23], v[198:199], s[68:69] op_sel_hi:[1,1,0]
	v_pk_fma_f32 v[212:213], v[26:27], v[212:213], s[68:69] op_sel_hi:[1,1,0]
	v_pk_fma_f32 v[226:227], v[30:31], v[226:227], s[68:69] op_sel_hi:[1,1,0]
	v_pk_mul_f32 v[180:181], v[112:113], v[180:181]
	v_pk_mul_f32 v[194:195], v[112:113], v[194:195]
	v_pk_mul_f32 v[208:209], v[112:113], v[208:209]
	v_pk_mul_f32 v[222:223], v[112:113], v[222:223]
	v_pk_fma_f32 v[184:185], v[18:19], v[184:185], 0.5 op_sel_hi:[1,1,0]
	v_pk_fma_f32 v[198:199], v[22:23], v[198:199], 0.5 op_sel_hi:[1,1,0]
	v_pk_fma_f32 v[212:213], v[26:27], v[212:213], 0.5 op_sel_hi:[1,1,0]
	v_pk_fma_f32 v[226:227], v[30:31], v[226:227], 0.5 op_sel_hi:[1,1,0]
	v_pk_fma_f32 v[178:179], v[180:181], s[62:63], v[178:179] op_sel_hi:[1,0,0]
	v_pk_fma_f32 v[192:193], v[194:195], s[62:63], v[192:193] op_sel_hi:[1,0,0]
	v_pk_fma_f32 v[206:207], v[208:209], s[62:63], v[206:207] op_sel_hi:[1,0,0]
	v_pk_fma_f32 v[220:221], v[222:223], s[62:63], v[220:221] op_sel_hi:[1,0,0]
	v_pk_fma_f32 v[184:185], v[18:19], v[184:185], 1.0 op_sel_hi:[1,1,0]
	v_pk_fma_f32 v[198:199], v[22:23], v[198:199], 1.0 op_sel_hi:[1,1,0]
	v_pk_fma_f32 v[212:213], v[26:27], v[212:213], 1.0 op_sel_hi:[1,1,0]
	v_pk_fma_f32 v[226:227], v[30:31], v[226:227], 1.0 op_sel_hi:[1,1,0]
	v_exp_f32_e32 v186, v186
	v_exp_f32_e32 v200, v200
	v_exp_f32_e32 v214, v214
	v_exp_f32_e32 v228, v228
	v_exp_f32_e32 v187, v187
	v_exp_f32_e32 v201, v201
	v_exp_f32_e32 v215, v215
	v_exp_f32_e32 v229, v229
	v_pk_fma_f32 v[178:179], v[180:181], v[178:179], s[66:67] op_sel_hi:[1,1,0]
	v_pk_fma_f32 v[192:193], v[194:195], v[192:193], s[66:67] op_sel_hi:[1,1,0]
	v_pk_fma_f32 v[206:207], v[208:209], v[206:207], s[66:67] op_sel_hi:[1,1,0]
	v_pk_fma_f32 v[220:221], v[222:223], v[220:221], s[66:67] op_sel_hi:[1,1,0]
	v_pk_fma_f32 v[188:189], v[182:183], v[182:183], 1.0 op_sel_hi:[1,1,0] neg_lo:[1,0,0] neg_hi:[1,0,0]
	v_pk_fma_f32 v[202:203], v[196:197], v[196:197], 1.0 op_sel_hi:[1,1,0] neg_lo:[1,0,0] neg_hi:[1,0,0]
	v_pk_fma_f32 v[216:217], v[210:211], v[210:211], 1.0 op_sel_hi:[1,1,0] neg_lo:[1,0,0] neg_hi:[1,0,0]
	v_pk_fma_f32 v[230:231], v[224:225], v[224:225], 1.0 op_sel_hi:[1,1,0] neg_lo:[1,0,0] neg_hi:[1,0,0]
	v_pk_mul_f32 v[184:185], v[18:19], v[184:185] neg_lo:[0,1] neg_hi:[0,1]
	v_pk_mul_f32 v[198:199], v[22:23], v[198:199] neg_lo:[0,1] neg_hi:[0,1]
	v_pk_mul_f32 v[212:213], v[26:27], v[212:213] neg_lo:[0,1] neg_hi:[0,1]
	v_pk_mul_f32 v[226:227], v[30:31], v[226:227] neg_lo:[0,1] neg_hi:[0,1]
	v_cmp_lt_f32_e64 s[16:17], s10, v19
	v_cmp_lt_f32_e64 s[18:19], s10, v18
	v_pk_fma_f32 v[178:179], v[180:181], v[178:179], s[68:69] op_sel_hi:[1,1,0]
	v_cndmask_b32_e64 v185, v189, v185, s[16:17]
	v_cndmask_b32_e64 v184, v188, v184, s[18:19]
	v_cmp_lt_f32_e64 s[16:17], s10, v23
	v_cmp_lt_f32_e64 s[18:19], s10, v22
	v_pk_fma_f32 v[192:193], v[194:195], v[192:193], s[68:69] op_sel_hi:[1,1,0]
	v_cndmask_b32_e64 v199, v203, v199, s[16:17]
	v_cndmask_b32_e64 v198, v202, v198, s[18:19]
	v_cmp_lt_f32_e64 s[16:17], s10, v27
	v_cmp_lt_f32_e64 s[18:19], s10, v26
	v_pk_fma_f32 v[206:207], v[208:209], v[206:207], s[68:69] op_sel_hi:[1,1,0]
	v_cndmask_b32_e64 v213, v217, v213, s[16:17]
	v_cndmask_b32_e64 v212, v216, v212, s[18:19]
	v_cmp_lt_f32_e64 s[16:17], s10, v31
	v_cmp_lt_f32_e64 s[18:19], s10, v30
	v_pk_fma_f32 v[220:221], v[222:223], v[220:221], s[68:69] op_sel_hi:[1,1,0]
	v_cndmask_b32_e64 v227, v231, v227, s[16:17]
	v_cndmask_b32_e64 v226, v230, v226, s[18:19]
	v_pk_fma_f32 v[178:179], v[180:181], v[178:179], 0.5 op_sel_hi:[1,1,0]
	v_pk_fma_f32 v[192:193], v[194:195], v[192:193], 0.5 op_sel_hi:[1,1,0]
	v_pk_fma_f32 v[206:207], v[208:209], v[206:207], 0.5 op_sel_hi:[1,1,0]
	v_pk_fma_f32 v[220:221], v[222:223], v[220:221], 0.5 op_sel_hi:[1,1,0]
	v_sqrt_f32_e32 v184, v184
	v_sqrt_f32_e32 v198, v198
	v_sqrt_f32_e32 v212, v212
	v_sqrt_f32_e32 v226, v226
	v_sqrt_f32_e32 v185, v185
	v_sqrt_f32_e32 v199, v199
	v_sqrt_f32_e32 v213, v213
	v_sqrt_f32_e32 v227, v227
	v_pk_fma_f32 v[178:179], v[180:181], v[178:179], 1.0 op_sel_hi:[1,1,0]
	v_pk_fma_f32 v[192:193], v[194:195], v[192:193], 1.0 op_sel_hi:[1,1,0]
	v_pk_fma_f32 v[206:207], v[208:209], v[206:207], 1.0 op_sel_hi:[1,1,0]
	v_pk_fma_f32 v[220:221], v[222:223], v[220:221], 1.0 op_sel_hi:[1,1,0]
	v_pk_fma_f32 v[18:19], v[186:187], v[186:187], 1.0 op_sel_hi:[1,1,0] neg_lo:[1,0,0] neg_hi:[1,0,0]
	v_pk_fma_f32 v[22:23], v[200:201], v[200:201], 1.0 op_sel_hi:[1,1,0] neg_lo:[1,0,0] neg_hi:[1,0,0]
	v_pk_fma_f32 v[26:27], v[214:215], v[214:215], 1.0 op_sel_hi:[1,1,0] neg_lo:[1,0,0] neg_hi:[1,0,0]
	v_pk_fma_f32 v[30:31], v[228:229], v[228:229], 1.0 op_sel_hi:[1,1,0] neg_lo:[1,0,0] neg_hi:[1,0,0]
	v_pk_mul_f32 v[178:179], v[180:181], v[178:179] neg_lo:[0,1] neg_hi:[0,1]
	v_pk_mul_f32 v[192:193], v[194:195], v[192:193] neg_lo:[0,1] neg_hi:[0,1]
	v_pk_mul_f32 v[206:207], v[208:209], v[206:207] neg_lo:[0,1] neg_hi:[0,1]
	v_pk_mul_f32 v[220:221], v[222:223], v[220:221] neg_lo:[0,1] neg_hi:[0,1]
	v_cmp_lt_f32_e64 s[16:17], s10, v181
	v_cmp_lt_f32_e64 s[18:19], s10, v180
	v_pk_mul_f32 v[16:17], v[16:17], v[184:185]
	v_cndmask_b32_e64 v179, v19, v179, s[16:17]
	v_cndmask_b32_e64 v178, v18, v178, s[18:19]
	v_cmp_lt_f32_e64 s[16:17], s10, v195
	v_cmp_lt_f32_e64 s[18:19], s10, v194
	v_pk_mul_f32 v[20:21], v[20:21], v[198:199]
	v_cndmask_b32_e64 v193, v23, v193, s[16:17]
	v_cndmask_b32_e64 v192, v22, v192, s[18:19]
	v_cmp_lt_f32_e64 s[16:17], s10, v209
	v_cmp_lt_f32_e64 s[18:19], s10, v208
	v_pk_mul_f32 v[24:25], v[24:25], v[212:213]
	v_cndmask_b32_e64 v207, v27, v207, s[16:17]
	v_cndmask_b32_e64 v206, v26, v206, s[18:19]
	v_cmp_lt_f32_e64 s[16:17], s10, v223
	v_cmp_lt_f32_e64 s[18:19], s10, v222
	v_pk_mul_f32 v[28:29], v[28:29], v[226:227]
	v_cndmask_b32_e64 v221, v31, v221, s[16:17]
	v_cndmask_b32_e64 v220, v30, v220, s[18:19]
	v_sqrt_f32_e32 v178, v178
	v_sqrt_f32_e32 v192, v192
	v_sqrt_f32_e32 v206, v206
	v_sqrt_f32_e32 v220, v220
	v_sqrt_f32_e32 v179, v179
	v_sqrt_f32_e32 v193, v193
	v_sqrt_f32_e32 v207, v207
	v_sqrt_f32_e32 v221, v221
	v_pk_mul_f32 v[16:17], v[152:153], v[16:17]
	v_pk_mul_f32 v[20:21], v[156:157], v[20:21]
	v_pk_mul_f32 v[24:25], v[160:161], v[24:25]
	v_pk_mul_f32 v[28:29], v[164:165], v[28:29]
	v_pk_mul_f32 v[178:179], v[2:3], v[178:179]
	v_pk_mul_f32 v[192:193], v[6:7], v[192:193]
	v_pk_mul_f32 v[206:207], v[10:11], v[206:207]
	v_pk_mul_f32 v[220:221], v[14:15], v[220:221]
	v_pk_mul_f32 v[178:179], v[154:155], v[178:179]
	v_pk_mul_f32 v[192:193], v[158:159], v[192:193]
	v_pk_mul_f32 v[206:207], v[162:163], v[206:207]
	v_pk_mul_f32 v[220:221], v[166:167], v[220:221]
	v_mul_f32_e32 v0, v182, v183
	v_fma_f32 v4, v183, v16, v17
	v_mul_f32_e32 v1, v196, v197
	v_fma_f32 v5, v197, v20, v21
	v_mul_f32_e32 v2, v210, v211
	v_fma_f32 v6, v211, v24, v25
	v_mul_f32_e32 v3, v224, v225
	v_fma_f32 v7, v225, v28, v29
	v_mul_f32_e32 v0, v0, v186
	v_fma_f32 v4, v186, v4, v178
	v_mul_f32_e32 v1, v1, v200
	v_fma_f32 v5, v200, v5, v192
	v_mul_f32_e32 v2, v2, v214
	v_fma_f32 v6, v214, v6, v206
	v_mul_f32_e32 v3, v3, v228
	v_fma_f32 v7, v228, v7, v220
	v_mul_f32_e32 v0, v0, v187
	v_fma_f32 v4, v187, v4, v179
	v_mul_f32_e32 v1, v1, v201
	v_fma_f32 v5, v201, v5, v193
	v_mul_f32_e32 v2, v2, v215
	v_fma_f32 v6, v215, v6, v207
	v_mul_f32_e32 v3, v3, v229
	v_fma_f32 v7, v229, v7, v221
	v_mov_b32_e32 v8, v0
	v_mov_b32_e32 v9, v1
	v_mov_b32_e32 v10, v2
	v_mov_b32_e32 v11, v3
	v_mov_b32_e32 v12, v4
	v_mov_b32_e32 v13, v5
	v_mov_b32_e32 v14, v6
	v_mov_b32_e32 v15, v7
	s_nop 1
	v_permlane32_swap_b32_e32 v0, v8
	v_permlane32_swap_b32_e32 v1, v9
	v_permlane32_swap_b32_e32 v2, v10
	v_permlane32_swap_b32_e32 v3, v11
	v_permlane32_swap_b32_e32 v4, v12
	v_permlane32_swap_b32_e32 v5, v13
	v_permlane32_swap_b32_e32 v6, v14
	v_permlane32_swap_b32_e32 v7, v15
	s_nop 0
	v_mov_b32_e32 v152, v0
	v_mov_b32_e32 v160, v4
	v_mul_f32_e32 v153, v8, v152
	v_fma_f32 v161, v8, v160, v12
	v_mul_f32_e32 v154, v1, v153
	v_fma_f32 v162, v1, v161, v5
	v_mul_f32_e32 v155, v9, v154
	v_fma_f32 v163, v9, v162, v13
	v_mul_f32_e32 v156, v2, v155
	v_fma_f32 v164, v2, v163, v6
	v_mul_f32_e32 v157, v10, v156
	v_fma_f32 v165, v10, v164, v14
	v_mul_f32_e32 v158, v3, v157
	v_fma_f32 v166, v3, v165, v7
	v_mul_f32_e32 v159, v11, v158
	v_fma_f32 v167, v11, v166, v15
	s_lshl_b32 s16, s24, 12
	s_and_b32 s16, s16, 0x1000
	s_add_i32 s16, s16, 0x20000
	s_lshr_b32 s17, s90, 5
	s_add_i32 s17, s17, s16
	v_lshl_add_u32 v251, v133, 2, s17
	v_lshl_add_u32 v177, v133, 2, s16
	ds_write2_b32 v251, v159, v167 offset1:32
	s_mov_b32 vcc_lo, 0
	s_mov_b32 vcc_hi, -1
	v_mov_b32_e32 v253, 1.0
	v_cndmask_b32_e32 v8, v253, v152, vcc
	v_cndmask_b32_e32 v12, 0, v160, vcc
	v_cndmask_b32_e32 v9, v153, v154, vcc
	v_cndmask_b32_e32 v13, v161, v162, vcc
	v_cndmask_b32_e32 v10, v155, v156, vcc
	v_cndmask_b32_e32 v14, v163, v164, vcc
	v_cndmask_b32_e32 v11, v157, v158, vcc
	v_cndmask_b32_e32 v15, v165, v166, vcc
	v_add_u32_e32 v253, 0x400, v177
	s_waitcnt lgkmcnt(0)
	s_barrier
	ds_read2_b32 v[152:153], v177 offset0:0 offset1:32
	ds_read2_b32 v[154:155], v177 offset0:64 offset1:96
	ds_read2_b32 v[156:157], v177 offset0:128 offset1:160
	ds_read2_b32 v[158:159], v177 offset0:192 offset1:224
	ds_read2_b32 v[160:161], v253 offset0:0 offset1:32
	ds_read2_b32 v[162:163], v253 offset0:64 offset1:96
	ds_read2_b32 v[164:165], v253 offset0:128 offset1:160
	ds_read2_b32 v[166:167], v253 offset0:192 offset1:224
	s_lshr_b32 s17, s90, 13
	v_mov_b32_e32 v251, v105
	s_cmp_eq_u32 s17, 0
	s_cselect_b64 s[18:19], -1, 0
	s_waitcnt lgkmcnt(7)
	v_cndmask_b32_e64 v251, v251, v105, s[18:19]
	v_fma_f32 v105, v152, v105, v153
	s_cmp_eq_u32 s17, 1
	s_cselect_b64 s[18:19], -1, 0
	s_waitcnt lgkmcnt(6)
	v_cndmask_b32_e64 v251, v251, v105, s[18:19]
	v_fma_f32 v105, v154, v105, v155
	s_cmp_eq_u32 s17, 2
	s_cselect_b64 s[18:19], -1, 0
	s_waitcnt lgkmcnt(5)
	v_cndmask_b32_e64 v251, v251, v105, s[18:19]
	v_fma_f32 v105, v156, v105, v157
	s_cmp_eq_u32 s17, 3
	s_cselect_b64 s[18:19], -1, 0
	s_waitcnt lgkmcnt(4)
	v_cndmask_b32_e64 v251, v251, v105, s[18:19]
	v_fma_f32 v105, v158, v105, v159
	s_cmp_eq_u32 s17, 4
	s_cselect_b64 s[18:19], -1, 0
	s_waitcnt lgkmcnt(3)
	v_cndmask_b32_e64 v251, v251, v105, s[18:19]
	v_fma_f32 v105, v160, v105, v161
	s_cmp_eq_u32 s17, 5
	s_cselect_b64 s[18:19], -1, 0
	s_waitcnt lgkmcnt(2)
	v_cndmask_b32_e64 v251, v251, v105, s[18:19]
	v_fma_f32 v105, v162, v105, v163
	s_cmp_eq_u32 s17, 6
	s_cselect_b64 s[18:19], -1, 0
	s_waitcnt lgkmcnt(1)
	v_cndmask_b32_e64 v251, v251, v105, s[18:19]
	v_fma_f32 v105, v164, v105, v165
	s_cmp_eq_u32 s17, 7
	s_cselect_b64 s[18:19], -1, 0
	s_waitcnt lgkmcnt(0)
	v_cndmask_b32_e64 v251, v251, v105, s[18:19]
	v_fma_f32 v105, v166, v105, v167
	v_fma_f32 v0, v8, v251, v12
	v_fma_f32 v1, v9, v251, v13
	v_fma_f32 v2, v10, v251, v14
	v_fma_f32 v3, v11, v251, v15
	v_fma_f32 v16, v182, v0, v16
	v_fma_f32 v20, v196, v1, v20
	v_fma_f32 v24, v210, v2, v24
	v_fma_f32 v28, v224, v3, v28
	v_fma_f32 v17, v183, v16, v17
	v_fma_f32 v21, v197, v20, v21
	v_fma_f32 v25, v211, v24, v25
	v_fma_f32 v29, v225, v28, v29
	v_fma_f32 v178, v186, v17, v178
	v_fma_f32 v192, v200, v21, v192
	v_fma_f32 v206, v214, v25, v206
	v_fma_f32 v220, v228, v29, v220
	v_fma_f32 v179, v187, v178, v179
	v_fma_f32 v193, v201, v192, v193
	v_fma_f32 v207, v215, v206, v207
	v_fma_f32 v221, v229, v220, v221
	ds_write_b32 v250, v16
	ds_write_b32 v250, v17 offset:128
	ds_write_b32 v250, v178 offset:256
	ds_write_b32 v250, v179 offset:384
	ds_write_b32 v250, v20 offset:1024
	ds_write_b32 v250, v21 offset:1152
	ds_write_b32 v250, v192 offset:1280
	ds_write_b32 v250, v193 offset:1408
	ds_write_b32 v250, v24 offset:2048
	ds_write_b32 v250, v25 offset:2176
	ds_write_b32 v250, v206 offset:2304
	ds_write_b32 v250, v207 offset:2432
	ds_write_b32 v250, v28 offset:3072
	ds_write_b32 v250, v29 offset:3200
	ds_write_b32 v250, v220 offset:3328
	ds_write_b32 v250, v221 offset:3456
	s_waitcnt lgkmcnt(0)
	v_lshlrev_b32_e32 v12, 7, v114
	v_lshlrev_b32_e32 v14, 6, v132
	s_waitcnt lgkmcnt(0)
	v_add3_u32 v12, s33, v12, v14
	ds_read_b128 v[14:17], v12
	ds_read_b128 v[18:21], v12 offset:16
	ds_read_b128 v[22:25], v12 offset:32
	ds_read_b128 v[26:29], v12 offset:48
	s_waitcnt lgkmcnt(3)
	v_mul_f32_e32 v12, v15, v15
	v_mul_f32_e32 v30, v17, v17
	v_fmac_f32_e32 v12, v14, v14
	v_fmac_f32_e32 v30, v16, v16
	v_add_f32_e32 v12, v12, v30
	s_waitcnt lgkmcnt(2)
	v_mul_f32_e32 v30, v19, v19
	v_fmac_f32_e32 v30, v18, v18
	v_add_f32_e32 v12, v12, v30
	v_mul_f32_e32 v30, v21, v21
	v_fmac_f32_e32 v30, v20, v20
	v_add_f32_e32 v12, v30, v12
	s_waitcnt lgkmcnt(1)
	v_mul_f32_e32 v30, v23, v23
	v_fmac_f32_e32 v30, v22, v22
	v_add_f32_e32 v12, v30, v12
	v_mul_f32_e32 v30, v25, v25
	v_fmac_f32_e32 v30, v24, v24
	v_add_f32_e32 v12, v30, v12
	s_waitcnt lgkmcnt(0)
	v_mul_f32_e32 v30, v27, v27
	v_fmac_f32_e32 v30, v26, v26
	v_add_f32_e32 v12, v30, v12
	v_mul_f32_e32 v30, v29, v29
	v_fmac_f32_e32 v30, v28, v28
	v_add_f32_e32 v12, v30, v12
	s_waitcnt vmcnt(0)
	v_lshlrev_b32_e32 v30, 16, v244
	v_and_b32_e32 v244, 0xffff0000, v244
	v_mul_f32_e32 v14, v14, v30
	v_mul_f32_e32 v244, v15, v244
	v_cvt_pk_bf16_f32 v244, v14, v244
	v_lshlrev_b32_e32 v14, 16, v245
	v_and_b32_e32 v245, 0xffff0000, v245
	v_mul_f32_e32 v14, v16, v14
	v_mul_f32_e32 v245, v17, v245
	v_cvt_pk_bf16_f32 v245, v14, v245
	v_lshlrev_b32_e32 v14, 16, v246
	v_and_b32_e32 v246, 0xffff0000, v246
	v_mul_f32_e32 v14, v18, v14
	v_mul_f32_e32 v246, v19, v246
	v_cvt_pk_bf16_f32 v246, v14, v246
	v_lshlrev_b32_e32 v14, 16, v247
	v_and_b32_e32 v247, 0xffff0000, v247
	v_mul_f32_e32 v14, v20, v14
	v_mul_f32_e32 v247, v21, v247
	v_cvt_pk_bf16_f32 v247, v14, v247
	v_lshlrev_b32_e32 v14, 16, v240
	v_and_b32_e32 v240, 0xffff0000, v240
	v_mul_f32_e32 v14, v22, v14
	v_mul_f32_e32 v240, v23, v240
	v_cvt_pk_bf16_f32 v14, v14, v240
	v_lshlrev_b32_e32 v240, 16, v241
	v_mul_f32_e32 v240, v24, v240
	v_and_b32_e32 v241, 0xffff0000, v241
	v_mul_f32_e32 v241, v25, v241
	v_cvt_pk_bf16_f32 v15, v240, v241
	v_lshlrev_b32_e32 v240, 16, v242
	v_mul_f32_e32 v240, v26, v240
	v_and_b32_e32 v241, 0xffff0000, v242
	v_mul_f32_e32 v241, v27, v241
	v_cvt_pk_bf16_f32 v16, v240, v241
	v_lshlrev_b32_e32 v240, 16, v243
	v_mul_f32_e32 v241, v28, v240
	v_and_b32_e32 v240, 0xffff0000, v243
	v_and_b32_e32 v243, 64, v126
	v_mul_f32_e32 v242, v29, v240
	v_xor_b32_e32 v240, 1, v126
	v_add_u32_e32 v243, 64, v243
	v_cmp_lt_i32_e64 s[16:17], v240, v243
	v_cvt_pk_bf16_f32 v17, v241, v242
	global_store_dwordx4 v[248:249], v[244:247], off
	global_store_dwordx4 v[248:249], v[14:17], off offset:16
	v_cndmask_b32_e64 v240, v126, v240, s[16:17]
	v_lshlrev_b32_e32 v240, 2, v240
	ds_bpermute_b32 v240, v240, v12
	v_cmp_eq_u32_e64 s[16:17], 0, v132
	s_and_saveexec_b64 s[18:19], s[16:17]
	s_cbranch_execz .LBB0_360
	s_lshl_b64 s[0:1], s[52:53], 2
	s_add_u32 s0, s25, s0
	s_addc_u32 s1, s26, s1
	v_ashrrev_i32_e32 v115, 31, v114
	v_lshl_add_u64 v[242:243], v[114:115], 2, s[0:1]
	s_waitcnt lgkmcnt(0)
	v_add_f32_e32 v240, v12, v240
	global_store_dword v[242:243], v240, off
	s_branch .LBB0_360

.LBB0_395:
	v_cndmask_b32_e64 v226, v178, v182, s[6:7]
	v_mul_f32_e32 v178, 0xbe0293ee, v226
	v_fmamk_f32 v50, v50, 0x3e0293ee, v178
	v_fmamk_f32 v51, v51, 0x3e0293ee, v178
	v_fmamk_f32 v52, v52, 0x3e0293ee, v178
	v_fmamk_f32 v53, v53, 0x3e0293ee, v178
	v_fmamk_f32 v54, v54, 0x3e0293ee, v178
	v_fmamk_f32 v55, v55, 0x3e0293ee, v178
	v_fmamk_f32 v56, v56, 0x3e0293ee, v178
	v_fmamk_f32 v57, v57, 0x3e0293ee, v178
	v_fmamk_f32 v58, v58, 0x3e0293ee, v178
	v_fmamk_f32 v59, v59, 0x3e0293ee, v178
	v_fmamk_f32 v60, v60, 0x3e0293ee, v178
	v_fmamk_f32 v61, v61, 0x3e0293ee, v178
	v_fmamk_f32 v62, v62, 0x3e0293ee, v178
	v_fmamk_f32 v63, v63, 0x3e0293ee, v178
	v_fmamk_f32 v64, v64, 0x3e0293ee, v178
	v_fmamk_f32 v65, v65, 0x3e0293ee, v178
	v_exp_f32_e32 v50, v50
	v_exp_f32_e32 v51, v51
	v_exp_f32_e32 v52, v52
	v_exp_f32_e32 v53, v53
	v_exp_f32_e32 v54, v54
	v_exp_f32_e32 v55, v55
	v_exp_f32_e32 v56, v56
	v_exp_f32_e32 v57, v57
	v_exp_f32_e32 v58, v58
	v_exp_f32_e32 v59, v59
	v_exp_f32_e32 v60, v60
	v_exp_f32_e32 v61, v61
	v_exp_f32_e32 v62, v62
	v_exp_f32_e32 v63, v63
	v_exp_f32_e32 v64, v64
	v_exp_f32_e32 v65, v65
	v_fmamk_f32 v82, v82, 0x3e0293ee, v178
	v_fmamk_f32 v83, v83, 0x3e0293ee, v178
	v_fmamk_f32 v84, v84, 0x3e0293ee, v178
	v_fmamk_f32 v85, v85, 0x3e0293ee, v178
	v_fmamk_f32 v86, v86, 0x3e0293ee, v178
	v_fmamk_f32 v87, v87, 0x3e0293ee, v178
	v_fmamk_f32 v88, v88, 0x3e0293ee, v178
	v_fmamk_f32 v89, v89, 0x3e0293ee, v178
	v_fmamk_f32 v90, v90, 0x3e0293ee, v178
	v_fmamk_f32 v91, v91, 0x3e0293ee, v178
	v_fmamk_f32 v92, v92, 0x3e0293ee, v178
	v_fmamk_f32 v93, v93, 0x3e0293ee, v178
	v_fmamk_f32 v94, v94, 0x3e0293ee, v178
	v_fmamk_f32 v95, v95, 0x3e0293ee, v178
	v_fmamk_f32 v96, v96, 0x3e0293ee, v178
	v_fmac_f32_e32 v178, 0x3e0293ee, v97
	s_waitcnt lgkmcnt(0)
	s_barrier
	ds_read_b128 v[230:233], v214 offset:32768
	ds_read_b128 v[234:237], v214 offset:40960
	ds_read_b128 v[238:241], v215 offset:32768
	ds_read_b128 v[242:245], v215 offset:40960
	ds_read_b128 v[180:183], v216 offset:32768
	ds_read_b128 v[184:187], v216 offset:40960
	ds_read_b128 v[246:249], v217 offset:32768
	ds_read_b128 v[250:253], v217 offset:40960
	v_exp_f32_e32 v97, v178
	v_add_f32_e32 v178, 0, v50
	v_add_f32_e32 v178, v51, v178
	s_waitcnt lgkmcnt(7)
	v_mfma_f32_32x32x16_bf16 v[114:129], v[230:233], v[158:161], v[114:129]
	v_add_f32_e32 v178, v52, v178
	v_add_f32_e32 v178, v53, v178
	v_add_f32_e32 v178, v54, v178
	v_add_f32_e32 v178, v55, v178
	v_add_f32_e32 v178, v56, v178
	v_add_f32_e32 v178, v57, v178
	v_add_f32_e32 v178, v58, v178
	s_waitcnt lgkmcnt(6)
	v_mfma_f32_32x32x16_bf16 v[98:113], v[234:237], v[158:161], v[98:113]
	ds_read_b128 v[230:233], v214 offset:32896
	ds_read_b128 v[234:237], v214 offset:41088
	v_add_f32_e32 v178, v59, v178
	v_add_f32_e32 v178, v60, v178
	v_add_f32_e32 v178, v61, v178
	v_exp_f32_e32 v82, v82
	v_add_f32_e32 v178, v62, v178
	v_exp_f32_e32 v83, v83
	s_waitcnt lgkmcnt(7)
	v_mfma_f32_32x32x16_bf16 v[114:129], v[238:241], v[154:157], v[114:129]
	v_add_f32_e32 v178, v63, v178
	v_exp_f32_e32 v84, v84
	v_add_f32_e32 v178, v64, v178
	v_exp_f32_e32 v85, v85
	v_add_f32_e32 v178, v65, v178
	v_exp_f32_e32 v86, v86
	v_add_f32_e32 v178, v82, v178
	s_waitcnt lgkmcnt(6)
	v_mfma_f32_32x32x16_bf16 v[98:113], v[242:245], v[154:157], v[98:113]
	ds_read_b128 v[238:241], v215 offset:32896
	ds_read_b128 v[242:245], v215 offset:41088
	v_exp_f32_e32 v87, v87
	v_add_f32_e32 v178, v83, v178
	v_exp_f32_e32 v88, v88
	v_add_f32_e32 v178, v84, v178
	v_exp_f32_e32 v89, v89
	v_add_f32_e32 v178, v85, v178
	s_waitcnt lgkmcnt(7)
	v_mfma_f32_32x32x16_bf16 v[114:129], v[180:183], v[150:153], v[114:129]
	v_exp_f32_e32 v90, v90
	v_add_f32_e32 v178, v86, v178
	v_exp_f32_e32 v91, v91
	v_add_f32_e32 v178, v87, v178
	v_exp_f32_e32 v92, v92
	v_add_f32_e32 v178, v88, v178
	v_exp_f32_e32 v93, v93
	s_waitcnt lgkmcnt(6)
	v_mfma_f32_32x32x16_bf16 v[98:113], v[184:187], v[150:153], v[98:113]
	ds_read_b128 v[180:183], v216 offset:32896
	ds_read_b128 v[184:187], v216 offset:41088
	v_add_f32_e32 v178, v89, v178
	v_exp_f32_e32 v94, v94
	v_add_f32_e32 v178, v90, v178
	v_exp_f32_e32 v95, v95
	v_add_f32_e32 v178, v91, v178
	v_exp_f32_e32 v96, v96
	s_waitcnt lgkmcnt(7)
	v_mfma_f32_32x32x16_bf16 v[114:129], v[246:249], v[146:149], v[114:129]
	v_add_f32_e32 v178, v92, v178
	v_add_f32_e32 v178, v93, v178
	v_add_f32_e32 v178, v94, v178
	v_add_f32_e32 v178, v95, v178
	v_add_f32_e32 v178, v96, v178
	v_add_f32_e32 v227, v97, v178
	v_mov_b32_e32 v228, v227
	s_waitcnt lgkmcnt(6)
	v_mfma_f32_32x32x16_bf16 v[98:113], v[250:253], v[146:149], v[98:113]
	ds_read_b128 v[246:249], v217 offset:32896
	ds_read_b128 v[250:253], v217 offset:41088
	v_permlane32_swap_b32_e32 v227, v228
	s_waitcnt lgkmcnt(7)
	v_mfma_f32_32x32x16_bf16 v[114:129], v[230:233], v[142:145], v[114:129]
	s_waitcnt lgkmcnt(6)
	v_mfma_f32_32x32x16_bf16 v[98:113], v[234:237], v[142:145], v[98:113]
	s_waitcnt lgkmcnt(5)
	v_mfma_f32_32x32x16_bf16 v[114:129], v[238:241], v[138:141], v[114:129]
	s_waitcnt lgkmcnt(4)
	v_mfma_f32_32x32x16_bf16 v[98:113], v[242:245], v[138:141], v[98:113]
	s_waitcnt lgkmcnt(3)
	v_mfma_f32_32x32x16_bf16 v[114:129], v[180:183], v[134:137], v[114:129]
	s_waitcnt lgkmcnt(2)
	v_mfma_f32_32x32x16_bf16 v[98:113], v[184:187], v[134:137], v[98:113]
	v_cvt_pk_bf16_f32 v178, v50, v51
	v_cvt_pk_bf16_f32 v179, v52, v53
	s_waitcnt lgkmcnt(1)
	v_mfma_f32_32x32x16_bf16 v[114:129], v[246:249], v[130:133], v[114:129]
	v_cvt_pk_bf16_f32 v180, v54, v55
	v_cvt_pk_bf16_f32 v181, v56, v57
	v_cvt_pk_bf16_f32 v182, v58, v59
	v_cvt_pk_bf16_f32 v183, v60, v61
	s_nop 0
	v_permlane32_swap_b32_e32 v178, v180
	s_waitcnt lgkmcnt(0)
	v_mfma_f32_32x32x16_bf16 v[98:113], v[250:253], v[130:133], v[98:113]
	v_cvt_pk_bf16_f32 v184, v62, v63
	v_cvt_pk_bf16_f32 v185, v64, v65
	v_cvt_pk_bf16_f32 v186, v82, v83
	v_cvt_pk_bf16_f32 v187, v84, v85
	v_cvt_pk_bf16_f32 v188, v86, v87
	v_cvt_pk_bf16_f32 v189, v88, v89
	v_cvt_pk_bf16_f32 v190, v90, v91
	v_cvt_pk_bf16_f32 v191, v92, v93
	v_cvt_pk_bf16_f32 v192, v94, v95
	v_cvt_pk_bf16_f32 v193, v96, v97
	v_permlane32_swap_b32_e32 v179, v181
	v_permlane32_swap_b32_e32 v182, v184
	v_permlane32_swap_b32_e32 v183, v185
	v_permlane32_swap_b32_e32 v186, v188
	v_permlane32_swap_b32_e32 v187, v189
	v_permlane32_swap_b32_e32 v190, v192
	v_permlane32_swap_b32_e32 v191, v193
	s_add_i32 s6, s33, 1
	s_cmp_lt_i32 s6, s27
	s_cselect_b64 s[54:55], -1, 0
	s_cmp_ge_i32 s6, s27
	s_cbranch_scc1 .LBB0_397
	global_load_dwordx4 v[50:53], v221, s[52:53]
	global_load_dwordx4 v[54:57], v221, s[52:53] offset:32
	global_load_dwordx4 v[82:85], v221, s[52:53] offset:128
	global_load_dwordx4 v[86:89], v221, s[52:53] offset:160
	global_load_dwordx4 v[58:61], v221, s[52:53] offset:64
	global_load_dwordx4 v[62:65], v221, s[52:53] offset:96
	global_load_dwordx4 v[90:93], v221, s[52:53] offset:192
	global_load_dwordx4 v[94:97], v221, s[52:53] offset:224
	v_add_u32_e32 v162, 0xffffff80, v229
	v_add_u32_e32 v164, 0xffffffa0, v229
	v_ashrrev_i32_e32 v163, 31, v162
	v_ashrrev_i32_e32 v165, 31, v164
	v_lshlrev_b64 v[170:171], 8, v[162:163]
	v_lshlrev_b64 v[172:173], 8, v[164:165]
	v_lshl_add_u64 v[162:163], v[196:197], 0, v[170:171]
	v_lshl_add_u64 v[166:167], v[196:197], 0, v[172:173]
	v_lshl_add_u64 v[170:171], v[198:199], 0, v[170:171]
	v_lshl_add_u64 v[174:175], v[198:199], 0, v[172:173]
	global_load_dwordx4 v[162:165], v[162:163], off
	s_nop 0
	global_load_dwordx4 v[166:169], v[166:167], off
	s_nop 0
	global_load_dwordx4 v[170:173], v[170:171], off
	s_nop 0
	global_load_dwordx4 v[174:177], v[174:175], off

.LBB0_497:
	s_waitcnt lgkmcnt(0)
	ds_read_b128 v[0:3], v147
	ds_read_b128 v[4:7], v147 offset:1024
	ds_read_b128 v[8:11], v147 offset:2048
	ds_read_b128 v[12:15], v147 offset:3072
	ds_read_b128 v[16:19], v148
	ds_read_b128 v[20:23], v148 offset:1024
	ds_read_b128 v[24:27], v148 offset:2048
	ds_read_b128 v[28:31], v148 offset:3072
	s_ashr_i32 s49, s48, 31
	s_lshl_b64 s[50:51], s[48:49], 17
	s_add_u32 s50, s68, s50
	s_addc_u32 s51, s69, s51
	s_and_b64 s[52:53], s[8:9], exec
	s_cselect_b32 s65, s51, s59
	s_cselect_b32 s64, s50, s58
	s_ashr_i32 s45, s44, 31
	s_lshl_b64 s[52:53], s[44:45], 17
	s_add_u32 s52, s72, s52
	s_addc_u32 s53, s73, s53
	s_and_b64 s[62:63], s[8:9], exec
	s_cselect_b32 s63, s53, s61
	s_cselect_b32 s62, s52, s60
	s_add_u32 s92, s58, 0x10080
	s_addc_u32 s93, s59, 0
	s_add_i32 s94, s81, 0xc000
	v_lshl_add_u64 v[64:65], s[92:93], 0, v[128:129]
	s_mov_b32 m0, s94
	s_add_i32 s45, s81, 0xe000
	ds_read_b128 v[32:35], v149
	ds_read_b128 v[36:39], v149 offset:1024
	ds_read_b128 v[40:43], v149 offset:2048
	ds_read_b128 v[44:47], v149 offset:3072
	ds_read_b128 v[48:51], v149 offset:4096
	ds_read_b128 v[52:55], v149 offset:5120
	ds_read_b128 v[56:59], v149 offset:6144
	ds_read_b128 v[60:63], v149 offset:7168
	global_load_lds_dwordx4 v[64:65], off
	v_lshl_add_u64 v[64:65], s[92:93], 0, v[132:133]
	s_mov_b32 m0, s45
	s_nop 0
	global_load_lds_dwordx4 v[64:65], off
	s_waitcnt vmcnt(8)
	s_waitcnt lgkmcnt(0)
	s_barrier
	s_waitcnt lgkmcnt(0)
	v_mfma_f32_16x16x32_bf16 v[64:67], v[0:3], v[32:35], 0
	v_mfma_f32_16x16x32_bf16 v[68:71], v[8:11], v[32:35], 0
	v_mfma_f32_16x16x32_bf16 v[72:75], v[0:3], v[40:43], 0
	v_mfma_f32_16x16x32_bf16 v[76:79], v[8:11], v[40:43], 0
	v_mfma_f32_16x16x32_bf16 v[80:83], v[0:3], v[48:51], 0
	v_mfma_f32_16x16x32_bf16 v[84:87], v[8:11], v[48:51], 0
	v_mfma_f32_16x16x32_bf16 v[88:91], v[0:3], v[56:59], 0
	v_mfma_f32_16x16x32_bf16 v[92:95], v[8:11], v[56:59], 0
	v_mfma_f32_16x16x32_bf16 v[64:67], v[4:7], v[36:39], v[64:67]
	v_mfma_f32_16x16x32_bf16 v[68:71], v[12:15], v[36:39], v[68:71]
	v_mfma_f32_16x16x32_bf16 v[72:75], v[4:7], v[44:47], v[72:75]
	v_mfma_f32_16x16x32_bf16 v[76:79], v[12:15], v[44:47], v[76:79]
	v_mfma_f32_16x16x32_bf16 v[80:83], v[4:7], v[52:55], v[80:83]
	v_mfma_f32_16x16x32_bf16 v[84:87], v[12:15], v[52:55], v[84:87]
	v_mfma_f32_16x16x32_bf16 v[88:91], v[4:7], v[60:63], v[88:91]
	v_mfma_f32_16x16x32_bf16 v[92:95], v[12:15], v[60:63], v[92:95]
	v_mfma_f32_16x16x32_bf16 v[96:99], v[16:19], v[32:35], 0
	v_mfma_f32_16x16x32_bf16 v[32:35], v[24:27], v[32:35], 0
	v_mfma_f32_16x16x32_bf16 v[96:99], v[20:23], v[36:39], v[96:99]
	v_mfma_f32_16x16x32_bf16 v[32:35], v[28:31], v[36:39], v[32:35]
	v_mfma_f32_16x16x32_bf16 v[36:39], v[16:19], v[40:43], 0
	v_mfma_f32_16x16x32_bf16 v[40:43], v[24:27], v[40:43], 0
	v_mfma_f32_16x16x32_bf16 v[36:39], v[20:23], v[44:47], v[36:39]
	v_mfma_f32_16x16x32_bf16 v[40:43], v[28:31], v[44:47], v[40:43]
	v_mfma_f32_16x16x32_bf16 v[44:47], v[16:19], v[48:51], 0
	v_mfma_f32_16x16x32_bf16 v[48:51], v[24:27], v[48:51], 0
	v_mfma_f32_16x16x32_bf16 v[44:47], v[20:23], v[52:55], v[44:47]
	v_mfma_f32_16x16x32_bf16 v[48:51], v[28:31], v[52:55], v[48:51]
	v_mfma_f32_16x16x32_bf16 v[52:55], v[16:19], v[56:59], 0
	v_mfma_f32_16x16x32_bf16 v[56:59], v[24:27], v[56:59], 0
	v_mfma_f32_16x16x32_bf16 v[52:55], v[20:23], v[60:63], v[52:55]
	v_mfma_f32_16x16x32_bf16 v[56:59], v[28:31], v[60:63], v[56:59]
	s_barrier
	s_add_i32 s92, s88, s80
	v_lshl_add_u64 v[212:213], s[60:61], 0, v[130:131]
	s_add_i32 s49, s92, 0x2000
	v_lshl_add_u64 v[140:141], v[212:213], 0, s[38:39]
	s_mov_b32 m0, s92
	v_lshl_add_u64 v[214:215], s[60:61], 0, v[134:135]
	s_add_u32 s96, s60, 0x10100
	ds_read_b128 v[60:63], v149 offset:16384
	ds_read_b128 v[100:103], v149 offset:17408
	ds_read_b128 v[104:107], v149 offset:18432
	ds_read_b128 v[108:111], v149 offset:19456
	ds_read_b128 v[112:115], v149 offset:20480
	ds_read_b128 v[116:119], v149 offset:21504
	ds_read_b128 v[120:123], v149 offset:22528
	ds_read_b128 v[124:127], v149 offset:23552
	global_load_lds_dwordx4 v[140:141], off
	v_lshl_add_u64 v[140:141], v[214:215], 0, s[38:39]
	s_mov_b32 m0, s49
	s_addc_u32 s97, s61, 0
	s_add_i32 s55, s89, s80
	global_load_lds_dwordx4 v[140:141], off
	v_lshl_add_u64 v[140:141], s[96:97], 0, v[130:131]
	s_mov_b32 m0, s55
	s_add_i32 s57, s55, 0x2000
	global_load_lds_dwordx4 v[140:141], off
	v_lshl_add_u64 v[140:141], s[96:97], 0, v[134:135]
	s_mov_b32 m0, s57
	v_lshl_add_u64 v[216:217], s[58:59], 0, v[128:129]
	global_load_lds_dwordx4 v[140:141], off
	v_lshl_add_u64 v[140:141], v[216:217], 0, s[38:39]
	s_mov_b32 m0, s81
	v_lshl_add_u64 v[218:219], s[58:59], 0, v[132:133]
	global_load_lds_dwordx4 v[140:141], off
	v_lshl_add_u64 v[140:141], v[218:219], 0, s[38:39]
	s_mov_b32 m0, s82
	s_nop 0
	global_load_lds_dwordx4 v[140:141], off
	s_waitcnt vmcnt(8)
	s_waitcnt lgkmcnt(0)
	s_barrier
	s_waitcnt lgkmcnt(0)
	v_mfma_f32_16x16x32_bf16 v[140:143], v[0:3], v[60:63], 0
	v_mfma_f32_16x16x32_bf16 v[156:159], v[0:3], v[104:107], 0
	v_mfma_f32_16x16x32_bf16 v[164:167], v[0:3], v[112:115], 0
	v_mfma_f32_16x16x32_bf16 v[0:3], v[0:3], v[120:123], 0
	v_mfma_f32_16x16x32_bf16 v[140:143], v[4:7], v[100:103], v[140:143]
	v_mfma_f32_16x16x32_bf16 v[156:159], v[4:7], v[108:111], v[156:159]
	v_mfma_f32_16x16x32_bf16 v[164:167], v[4:7], v[116:119], v[164:167]
	v_mfma_f32_16x16x32_bf16 v[0:3], v[4:7], v[124:127], v[0:3]
	v_mfma_f32_16x16x32_bf16 v[4:7], v[8:11], v[120:123], 0
	v_mfma_f32_16x16x32_bf16 v[152:155], v[8:11], v[60:63], 0
	v_mfma_f32_16x16x32_bf16 v[160:163], v[8:11], v[104:107], 0
	v_mfma_f32_16x16x32_bf16 v[168:171], v[8:11], v[112:115], 0
	v_mfma_f32_16x16x32_bf16 v[4:7], v[12:15], v[124:127], v[4:7]
	v_mfma_f32_16x16x32_bf16 v[152:155], v[12:15], v[100:103], v[152:155]
	v_mfma_f32_16x16x32_bf16 v[160:163], v[12:15], v[108:111], v[160:163]
	v_mfma_f32_16x16x32_bf16 v[168:171], v[12:15], v[116:119], v[168:171]
	v_mfma_f32_16x16x32_bf16 v[8:11], v[16:19], v[60:63], 0
	v_mfma_f32_16x16x32_bf16 v[12:15], v[24:27], v[60:63], 0
	v_mfma_f32_16x16x32_bf16 v[8:11], v[20:23], v[100:103], v[8:11]
	v_mfma_f32_16x16x32_bf16 v[12:15], v[28:31], v[100:103], v[12:15]
	v_mfma_f32_16x16x32_bf16 v[60:63], v[16:19], v[104:107], 0
	v_mfma_f32_16x16x32_bf16 v[100:103], v[24:27], v[104:107], 0
	v_mfma_f32_16x16x32_bf16 v[104:107], v[16:19], v[112:115], 0
	v_mfma_f32_16x16x32_bf16 v[16:19], v[16:19], v[120:123], 0
	v_mfma_f32_16x16x32_bf16 v[60:63], v[20:23], v[108:111], v[60:63]
	v_mfma_f32_16x16x32_bf16 v[100:103], v[28:31], v[108:111], v[100:103]
	v_mfma_f32_16x16x32_bf16 v[104:107], v[20:23], v[116:119], v[104:107]
	v_mfma_f32_16x16x32_bf16 v[108:111], v[24:27], v[112:115], 0
	v_mfma_f32_16x16x32_bf16 v[16:19], v[20:23], v[124:127], v[16:19]
	v_mfma_f32_16x16x32_bf16 v[20:23], v[24:27], v[120:123], 0
	v_mfma_f32_16x16x32_bf16 v[108:111], v[28:31], v[116:119], v[108:111]
	v_mfma_f32_16x16x32_bf16 v[20:23], v[28:31], v[124:127], v[20:23]
	s_barrier
	s_add_i32 s95, 0, 0x18000
	s_add_i32 vcc_lo, 0, 0x1c000
	v_add_u32_e32 v151, s95, v145
	v_add_u32_e32 v224, vcc_lo, v145
	ds_read_b128 v[24:27], v151
	ds_read_b128 v[28:31], v151 offset:1024
	ds_read_b128 v[112:115], v151 offset:2048
	ds_read_b128 v[116:119], v151 offset:3072
	ds_read_b128 v[120:123], v224
	ds_read_b128 v[124:127], v224 offset:1024
	ds_read_b128 v[172:175], v224 offset:2048
	ds_read_b128 v[176:179], v224 offset:3072
	s_add_u32 s96, s58, 0x10100
	s_addc_u32 s97, s59, 0
	s_mov_b32 m0, s83
	v_lshl_add_u64 v[220:221], s[96:97], 0, v[128:129]
	ds_read_b128 v[180:183], v149 offset:32768
	ds_read_b128 v[184:187], v149 offset:33792
	ds_read_b128 v[188:191], v149 offset:34816
	ds_read_b128 v[192:195], v149 offset:35840
	ds_read_b128 v[196:199], v149 offset:36864
	ds_read_b128 v[200:203], v149 offset:37888
	ds_read_b128 v[204:207], v149 offset:38912
	ds_read_b128 v[208:211], v149 offset:39936
	global_load_lds_dwordx4 v[220:221], off
	v_lshl_add_u64 v[220:221], s[96:97], 0, v[132:133]
	s_mov_b32 m0, s84
	s_nop 0
	global_load_lds_dwordx4 v[220:221], off
	s_waitcnt vmcnt(8)
	s_waitcnt lgkmcnt(0)
	s_barrier
	s_waitcnt lgkmcnt(0)
	v_mfma_f32_16x16x32_bf16 v[64:67], v[24:27], v[180:183], v[64:67]
	v_mfma_f32_16x16x32_bf16 v[68:71], v[112:115], v[180:183], v[68:71]
	v_mfma_f32_16x16x32_bf16 v[72:75], v[24:27], v[188:191], v[72:75]
	v_mfma_f32_16x16x32_bf16 v[76:79], v[112:115], v[188:191], v[76:79]
	v_mfma_f32_16x16x32_bf16 v[80:83], v[24:27], v[196:199], v[80:83]
	v_mfma_f32_16x16x32_bf16 v[84:87], v[112:115], v[196:199], v[84:87]
	v_mfma_f32_16x16x32_bf16 v[88:91], v[24:27], v[204:207], v[88:91]
	v_mfma_f32_16x16x32_bf16 v[92:95], v[112:115], v[204:207], v[92:95]
	v_mfma_f32_16x16x32_bf16 v[64:67], v[28:31], v[184:187], v[64:67]
	v_mfma_f32_16x16x32_bf16 v[68:71], v[116:119], v[184:187], v[68:71]
	v_mfma_f32_16x16x32_bf16 v[72:75], v[28:31], v[192:195], v[72:75]
	v_mfma_f32_16x16x32_bf16 v[76:79], v[116:119], v[192:195], v[76:79]
	v_mfma_f32_16x16x32_bf16 v[80:83], v[28:31], v[200:203], v[80:83]
	v_mfma_f32_16x16x32_bf16 v[84:87], v[116:119], v[200:203], v[84:87]
	v_mfma_f32_16x16x32_bf16 v[88:91], v[28:31], v[208:211], v[88:91]
	v_mfma_f32_16x16x32_bf16 v[92:95], v[116:119], v[208:211], v[92:95]
	v_mfma_f32_16x16x32_bf16 v[96:99], v[120:123], v[180:183], v[96:99]
	v_mfma_f32_16x16x32_bf16 v[32:35], v[172:175], v[180:183], v[32:35]
	v_mfma_f32_16x16x32_bf16 v[36:39], v[120:123], v[188:191], v[36:39]
	v_mfma_f32_16x16x32_bf16 v[40:43], v[172:175], v[188:191], v[40:43]
	v_mfma_f32_16x16x32_bf16 v[44:47], v[120:123], v[196:199], v[44:47]
	v_mfma_f32_16x16x32_bf16 v[48:51], v[172:175], v[196:199], v[48:51]
	v_mfma_f32_16x16x32_bf16 v[52:55], v[120:123], v[204:207], v[52:55]
	v_mfma_f32_16x16x32_bf16 v[56:59], v[172:175], v[204:207], v[56:59]
	v_mfma_f32_16x16x32_bf16 v[96:99], v[124:127], v[184:187], v[96:99]
	v_mfma_f32_16x16x32_bf16 v[32:35], v[176:179], v[184:187], v[32:35]
	v_mfma_f32_16x16x32_bf16 v[36:39], v[124:127], v[192:195], v[36:39]
	v_mfma_f32_16x16x32_bf16 v[40:43], v[176:179], v[192:195], v[40:43]
	v_mfma_f32_16x16x32_bf16 v[44:47], v[124:127], v[200:203], v[44:47]
	v_mfma_f32_16x16x32_bf16 v[48:51], v[176:179], v[200:203], v[48:51]
	v_mfma_f32_16x16x32_bf16 v[52:55], v[124:127], v[208:211], v[52:55]
	v_mfma_f32_16x16x32_bf16 v[56:59], v[176:179], v[208:211], v[56:59]
	s_barrier
	s_add_i32 s95, s95, s80
	s_add_i32 s93, s95, 0x2000
	v_lshl_add_u64 v[212:213], v[212:213], 0, s[40:41]
	s_mov_b32 m0, s95
	s_add_u32 s96, s60, 0x10180
	ds_read_b128 v[180:183], v149 offset:49152
	ds_read_b128 v[184:187], v149 offset:50176
	ds_read_b128 v[188:191], v149 offset:51200
	ds_read_b128 v[192:195], v149 offset:52224
	ds_read_b128 v[196:199], v149 offset:53248
	ds_read_b128 v[200:203], v149 offset:54272
	ds_read_b128 v[204:207], v149 offset:55296
	ds_read_b128 v[208:211], v149 offset:56320
	global_load_lds_dwordx4 v[212:213], off
	v_lshl_add_u64 v[212:213], v[214:215], 0, s[40:41]
	s_mov_b32 m0, s93
	s_addc_u32 s97, s61, 0
	s_add_i32 s60, vcc_lo, s80
	global_load_lds_dwordx4 v[212:213], off
	v_lshl_add_u64 v[212:213], s[96:97], 0, v[130:131]
	s_mov_b32 m0, s60
	s_add_i32 s61, s60, 0x2000
	global_load_lds_dwordx4 v[212:213], off
	v_lshl_add_u64 v[212:213], s[96:97], 0, v[134:135]
	s_mov_b32 m0, s61
	s_nop 0
	global_load_lds_dwordx4 v[212:213], off
	v_lshl_add_u64 v[212:213], v[216:217], 0, s[40:41]
	s_mov_b32 m0, s86
	s_nop 0
	global_load_lds_dwordx4 v[212:213], off
	v_lshl_add_u64 v[212:213], v[218:219], 0, s[40:41]
	s_mov_b32 m0, s87
	s_nop 0
	global_load_lds_dwordx4 v[212:213], off
	s_waitcnt vmcnt(8)
	s_waitcnt lgkmcnt(0)
	s_barrier
	s_waitcnt lgkmcnt(0)
	v_mfma_f32_16x16x32_bf16 v[0:3], v[24:27], v[204:207], v[0:3]
	v_mfma_f32_16x16x32_bf16 v[4:7], v[112:115], v[204:207], v[4:7]
	v_mfma_f32_16x16x32_bf16 v[140:143], v[24:27], v[180:183], v[140:143]
	v_mfma_f32_16x16x32_bf16 v[152:155], v[112:115], v[180:183], v[152:155]
	v_mfma_f32_16x16x32_bf16 v[156:159], v[24:27], v[188:191], v[156:159]
	v_mfma_f32_16x16x32_bf16 v[160:163], v[112:115], v[188:191], v[160:163]
	v_mfma_f32_16x16x32_bf16 v[164:167], v[24:27], v[196:199], v[164:167]
	v_mfma_f32_16x16x32_bf16 v[168:171], v[112:115], v[196:199], v[168:171]
	v_mfma_f32_16x16x32_bf16 v[0:3], v[28:31], v[208:211], v[0:3]
	v_mfma_f32_16x16x32_bf16 v[4:7], v[116:119], v[208:211], v[4:7]
	v_mfma_f32_16x16x32_bf16 v[140:143], v[28:31], v[184:187], v[140:143]
	v_mfma_f32_16x16x32_bf16 v[152:155], v[116:119], v[184:187], v[152:155]
	v_mfma_f32_16x16x32_bf16 v[156:159], v[28:31], v[192:195], v[156:159]
	v_mfma_f32_16x16x32_bf16 v[160:163], v[116:119], v[192:195], v[160:163]
	v_mfma_f32_16x16x32_bf16 v[164:167], v[28:31], v[200:203], v[164:167]
	v_mfma_f32_16x16x32_bf16 v[168:171], v[116:119], v[200:203], v[168:171]
	v_mfma_f32_16x16x32_bf16 v[8:11], v[120:123], v[180:183], v[8:11]
	v_mfma_f32_16x16x32_bf16 v[12:15], v[172:175], v[180:183], v[12:15]
	v_mfma_f32_16x16x32_bf16 v[24:27], v[120:123], v[188:191], v[60:63]
	v_mfma_f32_16x16x32_bf16 v[28:31], v[172:175], v[188:191], v[100:103]
	v_mfma_f32_16x16x32_bf16 v[60:63], v[120:123], v[196:199], v[104:107]
	v_mfma_f32_16x16x32_bf16 v[100:103], v[172:175], v[196:199], v[108:111]
	v_mfma_f32_16x16x32_bf16 v[16:19], v[120:123], v[204:207], v[16:19]
	v_mfma_f32_16x16x32_bf16 v[20:23], v[172:175], v[204:207], v[20:23]
	v_mfma_f32_16x16x32_bf16 v[8:11], v[124:127], v[184:187], v[8:11]
	v_mfma_f32_16x16x32_bf16 v[12:15], v[176:179], v[184:187], v[12:15]
	v_mfma_f32_16x16x32_bf16 v[24:27], v[124:127], v[192:195], v[24:27]
	v_mfma_f32_16x16x32_bf16 v[28:31], v[176:179], v[192:195], v[28:31]
	v_mfma_f32_16x16x32_bf16 v[60:63], v[124:127], v[200:203], v[60:63]
	v_mfma_f32_16x16x32_bf16 v[100:103], v[176:179], v[200:203], v[100:103]
	v_mfma_f32_16x16x32_bf16 v[16:19], v[124:127], v[208:211], v[16:19]
	v_mfma_f32_16x16x32_bf16 v[20:23], v[176:179], v[208:211], v[20:23]
	s_barrier
	ds_read_b128 v[104:107], v147
	ds_read_b128 v[108:111], v147 offset:1024
	ds_read_b128 v[112:115], v147 offset:2048
	ds_read_b128 v[116:119], v147 offset:3072
	ds_read_b128 v[120:123], v148
	ds_read_b128 v[124:127], v148 offset:1024
	ds_read_b128 v[172:175], v148 offset:2048
	ds_read_b128 v[176:179], v148 offset:3072
	s_add_u32 s58, s58, 0x10180
	s_addc_u32 s59, s59, 0
	s_mov_b32 m0, s94
	v_lshl_add_u64 v[212:213], s[58:59], 0, v[128:129]
	ds_read_b128 v[180:183], v149
	ds_read_b128 v[184:187], v149 offset:1024
	ds_read_b128 v[188:191], v149 offset:2048
	ds_read_b128 v[192:195], v149 offset:3072
	ds_read_b128 v[196:199], v149 offset:4096
	ds_read_b128 v[200:203], v149 offset:5120
	ds_read_b128 v[204:207], v149 offset:6144
	ds_read_b128 v[208:211], v149 offset:7168
	global_load_lds_dwordx4 v[212:213], off
	v_lshl_add_u64 v[212:213], s[58:59], 0, v[132:133]
	s_mov_b32 m0, s45
	s_nop 0
	global_load_lds_dwordx4 v[212:213], off
	s_waitcnt vmcnt(8)
	s_waitcnt lgkmcnt(0)
	s_barrier
	s_waitcnt lgkmcnt(0)
	v_mfma_f32_16x16x32_bf16 v[64:67], v[104:107], v[180:183], v[64:67]
	v_mfma_f32_16x16x32_bf16 v[68:71], v[112:115], v[180:183], v[68:71]
	v_mfma_f32_16x16x32_bf16 v[72:75], v[104:107], v[188:191], v[72:75]
	v_mfma_f32_16x16x32_bf16 v[76:79], v[112:115], v[188:191], v[76:79]
	v_mfma_f32_16x16x32_bf16 v[80:83], v[104:107], v[196:199], v[80:83]
	v_mfma_f32_16x16x32_bf16 v[84:87], v[112:115], v[196:199], v[84:87]
	v_mfma_f32_16x16x32_bf16 v[88:91], v[104:107], v[204:207], v[88:91]
	v_mfma_f32_16x16x32_bf16 v[64:67], v[108:111], v[184:187], v[64:67]
	v_mfma_f32_16x16x32_bf16 v[68:71], v[116:119], v[184:187], v[68:71]
	v_mfma_f32_16x16x32_bf16 v[72:75], v[108:111], v[192:195], v[72:75]
	v_mfma_f32_16x16x32_bf16 v[76:79], v[116:119], v[192:195], v[76:79]
	v_mfma_f32_16x16x32_bf16 v[80:83], v[108:111], v[200:203], v[80:83]
	v_mfma_f32_16x16x32_bf16 v[84:87], v[116:119], v[200:203], v[84:87]
	v_mfma_f32_16x16x32_bf16 v[212:215], v[108:111], v[208:211], v[88:91]
	v_mfma_f32_16x16x32_bf16 v[88:91], v[112:115], v[204:207], v[92:95]
	v_mfma_f32_16x16x32_bf16 v[216:219], v[116:119], v[208:211], v[88:91]
	v_mfma_f32_16x16x32_bf16 v[88:91], v[120:123], v[180:183], v[96:99]
	v_mfma_f32_16x16x32_bf16 v[32:35], v[172:175], v[180:183], v[32:35]
	v_mfma_f32_16x16x32_bf16 v[36:39], v[120:123], v[188:191], v[36:39]
	v_mfma_f32_16x16x32_bf16 v[40:43], v[172:175], v[188:191], v[40:43]
	v_mfma_f32_16x16x32_bf16 v[44:47], v[120:123], v[196:199], v[44:47]
	v_mfma_f32_16x16x32_bf16 v[48:51], v[172:175], v[196:199], v[48:51]
	v_mfma_f32_16x16x32_bf16 v[52:55], v[120:123], v[204:207], v[52:55]
	v_mfma_f32_16x16x32_bf16 v[56:59], v[172:175], v[204:207], v[56:59]
	v_mfma_f32_16x16x32_bf16 v[96:99], v[124:127], v[184:187], v[88:91]
	v_mfma_f32_16x16x32_bf16 v[32:35], v[176:179], v[184:187], v[32:35]
	v_mfma_f32_16x16x32_bf16 v[36:39], v[124:127], v[192:195], v[36:39]
	v_mfma_f32_16x16x32_bf16 v[40:43], v[176:179], v[192:195], v[40:43]
	v_mfma_f32_16x16x32_bf16 v[44:47], v[124:127], v[200:203], v[44:47]
	v_mfma_f32_16x16x32_bf16 v[48:51], v[176:179], v[200:203], v[48:51]
	v_mfma_f32_16x16x32_bf16 v[52:55], v[124:127], v[208:211], v[52:55]
	v_mfma_f32_16x16x32_bf16 v[56:59], v[176:179], v[208:211], v[56:59]
	s_barrier
	s_mov_b32 m0, s92
	v_lshl_add_u64 v[244:245], s[62:63], 0, v[130:131]
	s_add_u32 s58, s62, 0x10000
	ds_read_b128 v[88:91], v149 offset:16384
	ds_read_b128 v[92:95], v149 offset:17408
	ds_read_b128 v[180:183], v149 offset:18432
	ds_read_b128 v[184:187], v149 offset:19456
	ds_read_b128 v[188:191], v149 offset:20480
	ds_read_b128 v[192:195], v149 offset:21504
	ds_read_b128 v[196:199], v149 offset:22528
	ds_read_b128 v[200:203], v149 offset:23552
	global_load_lds_dwordx4 v[244:245], off
	v_lshl_add_u64 v[246:247], s[62:63], 0, v[134:135]
	s_mov_b32 m0, s49
	s_addc_u32 s59, s63, 0
	global_load_lds_dwordx4 v[246:247], off
	v_lshl_add_u64 v[204:205], s[58:59], 0, v[130:131]
	s_mov_b32 m0, s55
	v_lshl_add_u64 v[248:249], s[64:65], 0, v[128:129]
	global_load_lds_dwordx4 v[204:205], off
	v_lshl_add_u64 v[204:205], s[58:59], 0, v[134:135]
	s_mov_b32 m0, s57
	v_lshl_add_u64 v[250:251], s[64:65], 0, v[132:133]
	global_load_lds_dwordx4 v[204:205], off
	s_mov_b32 m0, s81
	s_nop 0
	global_load_lds_dwordx4 v[248:249], off
	s_mov_b32 m0, s82
	s_nop 0
	global_load_lds_dwordx4 v[250:251], off
	s_waitcnt vmcnt(8)
	s_waitcnt lgkmcnt(0)
	s_barrier
	s_waitcnt lgkmcnt(0)
	v_mfma_f32_16x16x32_bf16 v[0:3], v[104:107], v[196:199], v[0:3]
	v_mfma_f32_16x16x32_bf16 v[4:7], v[112:115], v[196:199], v[4:7]
	v_mfma_f32_16x16x32_bf16 v[140:143], v[104:107], v[88:91], v[140:143]
	v_mfma_f32_16x16x32_bf16 v[152:155], v[112:115], v[88:91], v[152:155]
	v_mfma_f32_16x16x32_bf16 v[156:159], v[104:107], v[180:183], v[156:159]
	v_mfma_f32_16x16x32_bf16 v[160:163], v[112:115], v[180:183], v[160:163]
	v_mfma_f32_16x16x32_bf16 v[164:167], v[104:107], v[188:191], v[164:167]
	v_mfma_f32_16x16x32_bf16 v[168:171], v[112:115], v[188:191], v[168:171]
	v_mfma_f32_16x16x32_bf16 v[0:3], v[108:111], v[200:203], v[0:3]
	v_mfma_f32_16x16x32_bf16 v[4:7], v[116:119], v[200:203], v[4:7]
	v_mfma_f32_16x16x32_bf16 v[140:143], v[108:111], v[92:95], v[140:143]
	v_mfma_f32_16x16x32_bf16 v[152:155], v[116:119], v[92:95], v[152:155]
	v_mfma_f32_16x16x32_bf16 v[156:159], v[108:111], v[184:187], v[156:159]
	v_mfma_f32_16x16x32_bf16 v[160:163], v[116:119], v[184:187], v[160:163]
	v_mfma_f32_16x16x32_bf16 v[164:167], v[108:111], v[192:195], v[164:167]
	v_mfma_f32_16x16x32_bf16 v[168:171], v[116:119], v[192:195], v[168:171]
	v_mfma_f32_16x16x32_bf16 v[8:11], v[120:123], v[88:91], v[8:11]
	v_mfma_f32_16x16x32_bf16 v[204:207], v[124:127], v[92:95], v[8:11]
	v_mfma_f32_16x16x32_bf16 v[8:11], v[172:175], v[88:91], v[12:15]
	v_mfma_f32_16x16x32_bf16 v[208:211], v[176:179], v[92:95], v[8:11]
	v_mfma_f32_16x16x32_bf16 v[8:11], v[120:123], v[180:183], v[24:27]
	v_mfma_f32_16x16x32_bf16 v[220:223], v[124:127], v[184:187], v[8:11]
	v_mfma_f32_16x16x32_bf16 v[8:11], v[172:175], v[180:183], v[28:31]
	v_mfma_f32_16x16x32_bf16 v[180:183], v[176:179], v[184:187], v[8:11]
	v_mfma_f32_16x16x32_bf16 v[8:11], v[120:123], v[188:191], v[60:63]
	v_mfma_f32_16x16x32_bf16 v[184:187], v[124:127], v[192:195], v[8:11]
	v_mfma_f32_16x16x32_bf16 v[8:11], v[172:175], v[188:191], v[100:103]
	v_mfma_f32_16x16x32_bf16 v[188:191], v[176:179], v[192:195], v[8:11]
	v_mfma_f32_16x16x32_bf16 v[8:11], v[120:123], v[196:199], v[16:19]
	v_mfma_f32_16x16x32_bf16 v[192:195], v[124:127], v[200:203], v[8:11]
	v_mfma_f32_16x16x32_bf16 v[8:11], v[172:175], v[196:199], v[20:23]
	v_mfma_f32_16x16x32_bf16 v[172:175], v[176:179], v[200:203], v[8:11]
	s_barrier
	s_nop 4
	ds_read_b128 v[8:11], v151
	ds_read_b128 v[12:15], v151 offset:1024
	ds_read_b128 v[16:19], v151 offset:2048
	ds_read_b128 v[20:23], v151 offset:3072
	ds_read_b128 v[176:179], v224
	ds_read_b128 v[196:199], v224 offset:1024
	ds_read_b128 v[200:203], v224 offset:2048
	ds_read_b128 v[224:227], v224 offset:3072
	s_add_u32 s58, s64, 0x10000
	s_addc_u32 s59, s65, 0
	s_mov_b32 m0, s83
	v_lshl_add_u64 v[88:89], s[58:59], 0, v[128:129]
	ds_read_b128 v[24:27], v149 offset:32768
	ds_read_b128 v[28:31], v149 offset:33792
	ds_read_b128 v[60:63], v149 offset:34816
	ds_read_b128 v[100:103], v149 offset:35840
	ds_read_b128 v[228:231], v149 offset:36864
	ds_read_b128 v[232:235], v149 offset:37888
	ds_read_b128 v[236:239], v149 offset:38912
	ds_read_b128 v[240:243], v149 offset:39936
	global_load_lds_dwordx4 v[88:89], off
	v_lshl_add_u64 v[88:89], s[58:59], 0, v[132:133]
	s_mov_b32 m0, s84
	s_nop 0
	global_load_lds_dwordx4 v[88:89], off
	s_waitcnt vmcnt(8)
	s_waitcnt lgkmcnt(0)
	s_barrier
	s_waitcnt lgkmcnt(0)
	v_mfma_f32_16x16x32_bf16 v[64:67], v[8:11], v[24:27], v[64:67]
	v_mfma_f32_16x16x32_bf16 v[120:123], v[12:15], v[28:31], v[64:67]
	v_mfma_f32_16x16x32_bf16 v[64:67], v[16:19], v[24:27], v[68:71]
	v_mfma_f32_16x16x32_bf16 v[124:127], v[20:23], v[28:31], v[64:67]
	v_mfma_f32_16x16x32_bf16 v[64:67], v[8:11], v[60:63], v[72:75]
	v_mfma_f32_16x16x32_bf16 v[104:107], v[12:15], v[100:103], v[64:67]
	v_mfma_f32_16x16x32_bf16 v[64:67], v[16:19], v[60:63], v[76:79]
	v_mfma_f32_16x16x32_bf16 v[108:111], v[20:23], v[100:103], v[64:67]
	v_mfma_f32_16x16x32_bf16 v[64:67], v[8:11], v[228:231], v[80:83]
	v_mfma_f32_16x16x32_bf16 v[88:91], v[12:15], v[232:235], v[64:67]
	v_mfma_f32_16x16x32_bf16 v[64:67], v[16:19], v[228:231], v[84:87]
	v_mfma_f32_16x16x32_bf16 v[92:95], v[20:23], v[232:235], v[64:67]
	v_mfma_f32_16x16x32_bf16 v[64:67], v[8:11], v[236:239], v[212:215]
	v_mfma_f32_16x16x32_bf16 v[72:75], v[12:15], v[240:243], v[64:67]
	v_mfma_f32_16x16x32_bf16 v[64:67], v[16:19], v[236:239], v[216:219]
	v_mfma_f32_16x16x32_bf16 v[76:79], v[20:23], v[240:243], v[64:67]
	v_mfma_f32_16x16x32_bf16 v[64:67], v[176:179], v[24:27], v[96:99]
	v_mfma_f32_16x16x32_bf16 v[24:27], v[200:203], v[24:27], v[32:35]
	v_mfma_f32_16x16x32_bf16 v[116:119], v[224:227], v[28:31], v[24:27]
	v_mfma_f32_16x16x32_bf16 v[24:27], v[176:179], v[60:63], v[36:39]
	v_mfma_f32_16x16x32_bf16 v[96:99], v[196:199], v[100:103], v[24:27]
	v_mfma_f32_16x16x32_bf16 v[24:27], v[200:203], v[60:63], v[40:43]
	v_mfma_f32_16x16x32_bf16 v[100:103], v[224:227], v[100:103], v[24:27]
	v_mfma_f32_16x16x32_bf16 v[24:27], v[176:179], v[228:231], v[44:47]
	v_mfma_f32_16x16x32_bf16 v[80:83], v[196:199], v[232:235], v[24:27]
	v_mfma_f32_16x16x32_bf16 v[24:27], v[200:203], v[228:231], v[48:51]
	v_mfma_f32_16x16x32_bf16 v[84:87], v[224:227], v[232:235], v[24:27]
	v_mfma_f32_16x16x32_bf16 v[24:27], v[176:179], v[236:239], v[52:55]
	v_mfma_f32_16x16x32_bf16 v[112:115], v[196:199], v[28:31], v[64:67]
	v_mfma_f32_16x16x32_bf16 v[64:67], v[196:199], v[240:243], v[24:27]
	v_mfma_f32_16x16x32_bf16 v[24:27], v[200:203], v[236:239], v[56:59]
	v_mfma_f32_16x16x32_bf16 v[68:71], v[224:227], v[240:243], v[24:27]
	s_barrier
	s_mov_b32 m0, s95
	s_nop 3
	v_lshl_add_u64 v[24:25], v[244:245], 0, s[18:19]
	s_add_u32 s58, s62, 0x10080
	ds_read_b128 v[32:35], v149 offset:49152
	ds_read_b128 v[36:39], v149 offset:50176
	ds_read_b128 v[212:215], v149 offset:51200
	ds_read_b128 v[216:219], v149 offset:52224
	ds_read_b128 v[228:231], v149 offset:53248
	ds_read_b128 v[232:235], v149 offset:54272
	ds_read_b128 v[236:239], v149 offset:55296
	ds_read_b128 v[240:243], v149 offset:56320
	global_load_lds_dwordx4 v[24:25], off
	v_lshl_add_u64 v[24:25], v[246:247], 0, s[18:19]
	s_mov_b32 m0, s93
	s_addc_u32 s59, s63, 0
	global_load_lds_dwordx4 v[24:25], off
	v_lshl_add_u64 v[24:25], s[58:59], 0, v[130:131]
	s_mov_b32 m0, s60
	s_nop 0
	global_load_lds_dwordx4 v[24:25], off
	v_lshl_add_u64 v[24:25], s[58:59], 0, v[134:135]
	s_mov_b32 m0, s61
	s_nop 0
	global_load_lds_dwordx4 v[24:25], off
	v_lshl_add_u64 v[24:25], v[248:249], 0, s[18:19]
	s_mov_b32 m0, s86
	s_nop 0
	global_load_lds_dwordx4 v[24:25], off
	v_lshl_add_u64 v[24:25], v[250:251], 0, s[18:19]
	s_mov_b32 m0, s87
	s_nop 0
	global_load_lds_dwordx4 v[24:25], off
	s_waitcnt vmcnt(8)
	s_waitcnt lgkmcnt(0)
	s_barrier
	s_waitcnt lgkmcnt(0)
	v_mfma_f32_16x16x32_bf16 v[24:27], v[8:11], v[32:35], v[140:143]
	v_mfma_f32_16x16x32_bf16 v[56:59], v[12:15], v[36:39], v[24:27]
	v_mfma_f32_16x16x32_bf16 v[24:27], v[16:19], v[32:35], v[152:155]
	v_mfma_f32_16x16x32_bf16 v[60:63], v[20:23], v[36:39], v[24:27]
	v_mfma_f32_16x16x32_bf16 v[24:27], v[8:11], v[212:215], v[156:159]
	v_mfma_f32_16x16x32_bf16 v[40:43], v[12:15], v[216:219], v[24:27]
	v_mfma_f32_16x16x32_bf16 v[24:27], v[16:19], v[212:215], v[160:163]
	v_mfma_f32_16x16x32_bf16 v[0:3], v[8:11], v[236:239], v[0:3]
	v_mfma_f32_16x16x32_bf16 v[44:47], v[20:23], v[216:219], v[24:27]
	v_mfma_f32_16x16x32_bf16 v[24:27], v[8:11], v[228:231], v[164:167]
	v_mfma_f32_16x16x32_bf16 v[28:31], v[16:19], v[228:231], v[168:171]
	v_mfma_f32_16x16x32_bf16 v[8:11], v[12:15], v[240:243], v[0:3]
	v_mfma_f32_16x16x32_bf16 v[0:3], v[16:19], v[236:239], v[4:7]
	v_mfma_f32_16x16x32_bf16 v[24:27], v[12:15], v[232:235], v[24:27]
	v_mfma_f32_16x16x32_bf16 v[28:31], v[20:23], v[232:235], v[28:31]
	v_mfma_f32_16x16x32_bf16 v[12:15], v[20:23], v[240:243], v[0:3]
	v_mfma_f32_16x16x32_bf16 v[0:3], v[176:179], v[32:35], v[204:207]
	v_mfma_f32_16x16x32_bf16 v[48:51], v[196:199], v[36:39], v[0:3]
	v_mfma_f32_16x16x32_bf16 v[0:3], v[200:203], v[32:35], v[208:211]
	v_mfma_f32_16x16x32_bf16 v[52:55], v[224:227], v[36:39], v[0:3]
	v_mfma_f32_16x16x32_bf16 v[0:3], v[176:179], v[212:215], v[220:223]
	v_mfma_f32_16x16x32_bf16 v[32:35], v[196:199], v[216:219], v[0:3]
	v_mfma_f32_16x16x32_bf16 v[0:3], v[200:203], v[212:215], v[180:183]
	v_mfma_f32_16x16x32_bf16 v[36:39], v[224:227], v[216:219], v[0:3]
	v_mfma_f32_16x16x32_bf16 v[0:3], v[176:179], v[228:231], v[184:187]
	v_mfma_f32_16x16x32_bf16 v[16:19], v[196:199], v[232:235], v[0:3]
	v_mfma_f32_16x16x32_bf16 v[0:3], v[200:203], v[228:231], v[188:191]
	v_mfma_f32_16x16x32_bf16 v[20:23], v[224:227], v[232:235], v[0:3]
	v_mfma_f32_16x16x32_bf16 v[0:3], v[176:179], v[236:239], v[192:195]
	v_mfma_f32_16x16x32_bf16 v[4:7], v[200:203], v[236:239], v[172:175]
	v_mfma_f32_16x16x32_bf16 v[0:3], v[196:199], v[240:243], v[0:3]
	v_mfma_f32_16x16x32_bf16 v[4:7], v[224:227], v[240:243], v[4:7]
	s_barrier
	s_andn2_b64 vcc, exec, s[24:25]
	s_cbranch_vccnz .LBB0_499
	s_barrier

.LBB0_546:
	v_add_u32_e32 v1, s80, v155
	ds_read_b128 v[146:149], v1
	ds_read_b128 v[150:153], v1 offset:1024
	ds_read_b128 v[162:165], v1 offset:2048
	ds_read_b128 v[166:169], v1 offset:3072
	v_add_u32_e32 v1, s81, v155
	ds_read_b128 v[170:173], v1
	ds_read_b128 v[174:177], v1 offset:1024
	ds_read_b128 v[178:181], v1 offset:2048
	ds_read_b128 v[182:185], v1 offset:3072
	s_and_b64 s[56:57], exec, s[56:57]
	s_cselect_b32 s57, s43, s91
	s_cselect_b32 s56, s89, s90
	s_add_u32 s96, s93, 0x40000
	s_addc_u32 s97, s94, 0
	v_lshl_add_u64 v[2:3], s[96:97], 0, v[132:133]
	s_add_i32 m0, s9, 0xc000
	ds_read_b128 v[186:189], v159
	ds_read_b128 v[190:193], v159 offset:1024
	ds_read_b128 v[194:197], v159 offset:2048
	ds_read_b128 v[198:201], v159 offset:3072
	ds_read_b128 v[202:205], v159 offset:4096
	ds_read_b128 v[206:209], v159 offset:5120
	ds_read_b128 v[210:213], v159 offset:6144
	ds_read_b128 v[214:217], v159 offset:7168
	global_load_lds_dwordx4 v[2:3], off
	v_lshl_add_u64 v[2:3], s[96:97], 0, v[136:137]
	s_add_i32 m0, s9, 0xe000
	s_nop 0
	global_load_lds_dwordx4 v[2:3], off
	s_waitcnt vmcnt(8)
	s_waitcnt lgkmcnt(0)
	s_barrier
	s_waitcnt lgkmcnt(0)
	v_mfma_f32_16x16x32_bf16 v[128:131], v[146:149], v[186:189], v[128:131]
	v_mfma_f32_16x16x32_bf16 v[124:127], v[162:165], v[186:189], v[124:127]
	v_mfma_f32_16x16x32_bf16 v[112:115], v[146:149], v[194:197], v[112:115]
	v_mfma_f32_16x16x32_bf16 v[108:111], v[162:165], v[194:197], v[108:111]
	v_mfma_f32_16x16x32_bf16 v[96:99], v[146:149], v[202:205], v[96:99]
	v_mfma_f32_16x16x32_bf16 v[92:95], v[162:165], v[202:205], v[92:95]
	v_mfma_f32_16x16x32_bf16 v[80:83], v[146:149], v[210:213], v[80:83]
	v_mfma_f32_16x16x32_bf16 v[76:79], v[162:165], v[210:213], v[76:79]
	v_mfma_f32_16x16x32_bf16 v[128:131], v[150:153], v[190:193], v[128:131]
	v_mfma_f32_16x16x32_bf16 v[124:127], v[166:169], v[190:193], v[124:127]
	v_mfma_f32_16x16x32_bf16 v[112:115], v[150:153], v[198:201], v[112:115]
	v_mfma_f32_16x16x32_bf16 v[108:111], v[166:169], v[198:201], v[108:111]
	v_mfma_f32_16x16x32_bf16 v[96:99], v[150:153], v[206:209], v[96:99]
	v_mfma_f32_16x16x32_bf16 v[92:95], v[166:169], v[206:209], v[92:95]
	v_mfma_f32_16x16x32_bf16 v[80:83], v[150:153], v[214:217], v[80:83]
	v_mfma_f32_16x16x32_bf16 v[76:79], v[166:169], v[214:217], v[76:79]
	v_mfma_f32_16x16x32_bf16 v[120:123], v[170:173], v[186:189], v[120:123]
	v_mfma_f32_16x16x32_bf16 v[116:119], v[178:181], v[186:189], v[116:119]
	v_mfma_f32_16x16x32_bf16 v[104:107], v[170:173], v[194:197], v[104:107]
	v_mfma_f32_16x16x32_bf16 v[100:103], v[178:181], v[194:197], v[100:103]
	v_mfma_f32_16x16x32_bf16 v[88:91], v[170:173], v[202:205], v[88:91]
	v_mfma_f32_16x16x32_bf16 v[84:87], v[178:181], v[202:205], v[84:87]
	v_mfma_f32_16x16x32_bf16 v[72:75], v[170:173], v[210:213], v[72:75]
	v_mfma_f32_16x16x32_bf16 v[68:71], v[178:181], v[210:213], v[68:71]
	v_mfma_f32_16x16x32_bf16 v[120:123], v[174:177], v[190:193], v[120:123]
	v_mfma_f32_16x16x32_bf16 v[116:119], v[182:185], v[190:193], v[116:119]
	v_mfma_f32_16x16x32_bf16 v[104:107], v[174:177], v[198:201], v[104:107]
	v_mfma_f32_16x16x32_bf16 v[100:103], v[182:185], v[198:201], v[100:103]
	v_mfma_f32_16x16x32_bf16 v[88:91], v[174:177], v[206:209], v[88:91]
	v_mfma_f32_16x16x32_bf16 v[84:87], v[182:185], v[206:209], v[84:87]
	v_mfma_f32_16x16x32_bf16 v[72:75], v[174:177], v[214:217], v[72:75]
	v_mfma_f32_16x16x32_bf16 v[68:71], v[182:185], v[214:217], v[68:71]
	s_barrier
	s_add_i32 s14, s80, s0
	v_lshl_add_u64 v[218:219], s[56:57], 0, v[134:135]
	s_mov_b32 m0, s14
	ds_read_b128 v[186:189], v159 offset:16384
	ds_read_b128 v[190:193], v159 offset:17408
	ds_read_b128 v[194:197], v159 offset:18432
	ds_read_b128 v[198:201], v159 offset:19456
	ds_read_b128 v[202:205], v159 offset:20480
	ds_read_b128 v[206:209], v159 offset:21504
	ds_read_b128 v[210:213], v159 offset:22528
	ds_read_b128 v[214:217], v159 offset:23552
	global_load_lds_dwordx4 v[218:219], off
	s_add_i32 m0, s14, 0x2000
	s_add_u32 s94, s56, 0x80000
	v_lshl_add_u64 v[220:221], s[56:57], 0, v[138:139]
	s_addc_u32 s95, s57, 0
	s_add_i32 s14, s81, s0
	global_load_lds_dwordx4 v[220:221], off
	v_lshl_add_u64 v[2:3], s[94:95], 0, v[134:135]
	s_mov_b32 m0, s14
	v_lshl_add_u64 v[222:223], s[58:59], 0, v[132:133]
	global_load_lds_dwordx4 v[2:3], off
	v_lshl_add_u64 v[2:3], s[94:95], 0, v[138:139]
	s_add_i32 m0, s14, 0x2000
	v_lshl_add_u64 v[224:225], s[58:59], 0, v[136:137]
	global_load_lds_dwordx4 v[2:3], off
	s_mov_b32 m0, s9
	s_nop 0
	global_load_lds_dwordx4 v[222:223], off
	s_mov_b32 m0, s62
	s_nop 0
	global_load_lds_dwordx4 v[224:225], off
	s_waitcnt vmcnt(8)
	s_waitcnt lgkmcnt(0)
	s_barrier
	s_waitcnt lgkmcnt(0)
	v_mfma_f32_16x16x32_bf16 v[64:67], v[146:149], v[186:189], v[64:67]
	v_mfma_f32_16x16x32_bf16 v[60:63], v[162:165], v[186:189], v[60:63]
	v_mfma_f32_16x16x32_bf16 v[48:51], v[146:149], v[194:197], v[48:51]
	v_mfma_f32_16x16x32_bf16 v[44:47], v[162:165], v[194:197], v[44:47]
	v_mfma_f32_16x16x32_bf16 v[32:35], v[146:149], v[202:205], v[32:35]
	v_mfma_f32_16x16x32_bf16 v[28:31], v[162:165], v[202:205], v[28:31]
	v_mfma_f32_16x16x32_bf16 v[16:19], v[146:149], v[210:213], v[16:19]
	v_mfma_f32_16x16x32_bf16 v[12:15], v[162:165], v[210:213], v[12:15]
	v_mfma_f32_16x16x32_bf16 v[64:67], v[150:153], v[190:193], v[64:67]
	v_mfma_f32_16x16x32_bf16 v[60:63], v[166:169], v[190:193], v[60:63]
	v_mfma_f32_16x16x32_bf16 v[48:51], v[150:153], v[198:201], v[48:51]
	v_mfma_f32_16x16x32_bf16 v[44:47], v[166:169], v[198:201], v[44:47]
	v_mfma_f32_16x16x32_bf16 v[32:35], v[150:153], v[206:209], v[32:35]
	v_mfma_f32_16x16x32_bf16 v[28:31], v[166:169], v[206:209], v[28:31]
	v_mfma_f32_16x16x32_bf16 v[16:19], v[150:153], v[214:217], v[16:19]
	v_mfma_f32_16x16x32_bf16 v[12:15], v[166:169], v[214:217], v[12:15]
	v_mfma_f32_16x16x32_bf16 v[56:59], v[170:173], v[186:189], v[56:59]
	v_mfma_f32_16x16x32_bf16 v[52:55], v[178:181], v[186:189], v[52:55]
	v_mfma_f32_16x16x32_bf16 v[40:43], v[170:173], v[194:197], v[40:43]
	v_mfma_f32_16x16x32_bf16 v[36:39], v[178:181], v[194:197], v[36:39]
	v_mfma_f32_16x16x32_bf16 v[24:27], v[170:173], v[202:205], v[24:27]
	v_mfma_f32_16x16x32_bf16 v[20:23], v[178:181], v[202:205], v[20:23]
	v_mfma_f32_16x16x32_bf16 v[8:11], v[170:173], v[210:213], v[8:11]
	v_mfma_f32_16x16x32_bf16 v[2:5], v[178:181], v[210:213], v[4:7]
	v_mfma_f32_16x16x32_bf16 v[56:59], v[174:177], v[190:193], v[56:59]
	v_mfma_f32_16x16x32_bf16 v[52:55], v[182:185], v[190:193], v[52:55]
	v_mfma_f32_16x16x32_bf16 v[40:43], v[174:177], v[198:201], v[40:43]
	v_mfma_f32_16x16x32_bf16 v[36:39], v[182:185], v[198:201], v[36:39]
	v_mfma_f32_16x16x32_bf16 v[24:27], v[174:177], v[206:209], v[24:27]
	v_mfma_f32_16x16x32_bf16 v[20:23], v[182:185], v[206:209], v[20:23]
	v_mfma_f32_16x16x32_bf16 v[8:11], v[174:177], v[214:217], v[8:11]
	v_mfma_f32_16x16x32_bf16 v[2:5], v[182:185], v[214:217], v[2:5]
	s_barrier
	s_add_i32 s14, 0, 0x18000
	v_add_u32_e32 v1, s14, v155
	s_add_i32 s93, 0, 0x1c000
	ds_read_b128 v[146:149], v1
	ds_read_b128 v[150:153], v1 offset:1024
	ds_read_b128 v[162:165], v1 offset:2048
	ds_read_b128 v[166:169], v1 offset:3072
	v_add_u32_e32 v1, s93, v155
	ds_read_b128 v[170:173], v1
	ds_read_b128 v[174:177], v1 offset:1024
	ds_read_b128 v[178:181], v1 offset:2048
	ds_read_b128 v[182:185], v1 offset:3072
	s_add_u32 s58, s58, 0x40000
	s_addc_u32 s59, s59, 0
	s_mov_b32 m0, s63
	v_lshl_add_u64 v[6:7], s[58:59], 0, v[132:133]
	ds_read_b128 v[186:189], v159 offset:32768
	ds_read_b128 v[190:193], v159 offset:33792
	ds_read_b128 v[194:197], v159 offset:34816
	ds_read_b128 v[198:201], v159 offset:35840
	ds_read_b128 v[202:205], v159 offset:36864
	ds_read_b128 v[206:209], v159 offset:37888
	ds_read_b128 v[210:213], v159 offset:38912
	ds_read_b128 v[214:217], v159 offset:39936
	global_load_lds_dwordx4 v[6:7], off
	v_lshl_add_u64 v[6:7], s[58:59], 0, v[136:137]
	s_mov_b32 m0, s64
	s_nop 0
	global_load_lds_dwordx4 v[6:7], off
	s_waitcnt vmcnt(8)
	s_waitcnt lgkmcnt(0)
	s_barrier
	s_waitcnt lgkmcnt(0)
	v_mfma_f32_16x16x32_bf16 v[128:131], v[146:149], v[186:189], v[128:131]
	v_mfma_f32_16x16x32_bf16 v[124:127], v[162:165], v[186:189], v[124:127]
	v_mfma_f32_16x16x32_bf16 v[112:115], v[146:149], v[194:197], v[112:115]
	v_mfma_f32_16x16x32_bf16 v[108:111], v[162:165], v[194:197], v[108:111]
	v_mfma_f32_16x16x32_bf16 v[96:99], v[146:149], v[202:205], v[96:99]
	v_mfma_f32_16x16x32_bf16 v[92:95], v[162:165], v[202:205], v[92:95]
	v_mfma_f32_16x16x32_bf16 v[80:83], v[146:149], v[210:213], v[80:83]
	v_mfma_f32_16x16x32_bf16 v[76:79], v[162:165], v[210:213], v[76:79]
	v_mfma_f32_16x16x32_bf16 v[128:131], v[150:153], v[190:193], v[128:131]
	v_mfma_f32_16x16x32_bf16 v[124:127], v[166:169], v[190:193], v[124:127]
	v_mfma_f32_16x16x32_bf16 v[112:115], v[150:153], v[198:201], v[112:115]
	v_mfma_f32_16x16x32_bf16 v[108:111], v[166:169], v[198:201], v[108:111]
	v_mfma_f32_16x16x32_bf16 v[96:99], v[150:153], v[206:209], v[96:99]
	v_mfma_f32_16x16x32_bf16 v[92:95], v[166:169], v[206:209], v[92:95]
	v_mfma_f32_16x16x32_bf16 v[80:83], v[150:153], v[214:217], v[80:83]
	v_mfma_f32_16x16x32_bf16 v[76:79], v[166:169], v[214:217], v[76:79]
	v_mfma_f32_16x16x32_bf16 v[120:123], v[170:173], v[186:189], v[120:123]
	v_mfma_f32_16x16x32_bf16 v[116:119], v[178:181], v[186:189], v[116:119]
	v_mfma_f32_16x16x32_bf16 v[104:107], v[170:173], v[194:197], v[104:107]
	v_mfma_f32_16x16x32_bf16 v[100:103], v[178:181], v[194:197], v[100:103]
	v_mfma_f32_16x16x32_bf16 v[88:91], v[170:173], v[202:205], v[88:91]
	v_mfma_f32_16x16x32_bf16 v[84:87], v[178:181], v[202:205], v[84:87]
	v_mfma_f32_16x16x32_bf16 v[72:75], v[170:173], v[210:213], v[72:75]
	v_mfma_f32_16x16x32_bf16 v[68:71], v[178:181], v[210:213], v[68:71]
	v_mfma_f32_16x16x32_bf16 v[120:123], v[174:177], v[190:193], v[120:123]
	v_mfma_f32_16x16x32_bf16 v[116:119], v[182:185], v[190:193], v[116:119]
	v_mfma_f32_16x16x32_bf16 v[104:107], v[174:177], v[198:201], v[104:107]
	v_mfma_f32_16x16x32_bf16 v[100:103], v[182:185], v[198:201], v[100:103]
	v_mfma_f32_16x16x32_bf16 v[88:91], v[174:177], v[206:209], v[88:91]
	v_mfma_f32_16x16x32_bf16 v[84:87], v[182:185], v[206:209], v[84:87]
	v_mfma_f32_16x16x32_bf16 v[72:75], v[174:177], v[214:217], v[72:75]
	v_mfma_f32_16x16x32_bf16 v[68:71], v[182:185], v[214:217], v[68:71]
	s_barrier
	s_add_i32 s14, s14, s0
	v_lshl_add_u64 v[6:7], v[218:219], 0, s[24:25]
	s_mov_b32 m0, s14
	ds_read_b128 v[186:189], v159 offset:49152
	ds_read_b128 v[190:193], v159 offset:50176
	ds_read_b128 v[194:197], v159 offset:51200
	ds_read_b128 v[198:201], v159 offset:52224
	ds_read_b128 v[202:205], v159 offset:53248
	ds_read_b128 v[206:209], v159 offset:54272
	ds_read_b128 v[210:213], v159 offset:55296
	ds_read_b128 v[214:217], v159 offset:56320
	global_load_lds_dwordx4 v[6:7], off
	s_add_i32 m0, s14, 0x2000
	s_add_u32 s56, s56, 0x80080
	v_lshl_add_u64 v[6:7], v[220:221], 0, s[24:25]
	s_addc_u32 s57, s57, 0
	s_add_i32 s14, s93, s0
	global_load_lds_dwordx4 v[6:7], off
	v_lshl_add_u64 v[6:7], s[56:57], 0, v[134:135]
	s_mov_b32 m0, s14
	s_nop 0
	global_load_lds_dwordx4 v[6:7], off
	v_lshl_add_u64 v[6:7], s[56:57], 0, v[138:139]
	s_add_i32 m0, s14, 0x2000
	s_nop 0
	global_load_lds_dwordx4 v[6:7], off
	v_lshl_add_u64 v[6:7], v[222:223], 0, s[24:25]
	s_mov_b32 m0, s72
	s_nop 0
	global_load_lds_dwordx4 v[6:7], off
	v_lshl_add_u64 v[6:7], v[224:225], 0, s[24:25]
	s_mov_b32 m0, s73
	s_nop 0
	global_load_lds_dwordx4 v[6:7], off
	s_waitcnt vmcnt(8)
	s_waitcnt lgkmcnt(0)
	s_barrier
	s_waitcnt lgkmcnt(0)
	v_mfma_f32_16x16x32_bf16 v[64:67], v[146:149], v[186:189], v[64:67]
	v_mfma_f32_16x16x32_bf16 v[60:63], v[162:165], v[186:189], v[60:63]
	v_mfma_f32_16x16x32_bf16 v[48:51], v[146:149], v[194:197], v[48:51]
	v_mfma_f32_16x16x32_bf16 v[44:47], v[162:165], v[194:197], v[44:47]
	v_mfma_f32_16x16x32_bf16 v[32:35], v[146:149], v[202:205], v[32:35]
	v_mfma_f32_16x16x32_bf16 v[28:31], v[162:165], v[202:205], v[28:31]
	v_mfma_f32_16x16x32_bf16 v[16:19], v[146:149], v[210:213], v[16:19]
	v_mfma_f32_16x16x32_bf16 v[12:15], v[162:165], v[210:213], v[12:15]
	v_mfma_f32_16x16x32_bf16 v[64:67], v[150:153], v[190:193], v[64:67]
	v_mfma_f32_16x16x32_bf16 v[60:63], v[166:169], v[190:193], v[60:63]
	v_mfma_f32_16x16x32_bf16 v[48:51], v[150:153], v[198:201], v[48:51]
	v_mfma_f32_16x16x32_bf16 v[44:47], v[166:169], v[198:201], v[44:47]
	v_mfma_f32_16x16x32_bf16 v[32:35], v[150:153], v[206:209], v[32:35]
	v_mfma_f32_16x16x32_bf16 v[28:31], v[166:169], v[206:209], v[28:31]
	v_mfma_f32_16x16x32_bf16 v[16:19], v[150:153], v[214:217], v[16:19]
	v_mfma_f32_16x16x32_bf16 v[12:15], v[166:169], v[214:217], v[12:15]
	v_mfma_f32_16x16x32_bf16 v[56:59], v[170:173], v[186:189], v[56:59]
	v_mfma_f32_16x16x32_bf16 v[52:55], v[178:181], v[186:189], v[52:55]
	v_mfma_f32_16x16x32_bf16 v[40:43], v[170:173], v[194:197], v[40:43]
	v_mfma_f32_16x16x32_bf16 v[36:39], v[178:181], v[194:197], v[36:39]
	v_mfma_f32_16x16x32_bf16 v[24:27], v[170:173], v[202:205], v[24:27]
	v_mfma_f32_16x16x32_bf16 v[20:23], v[178:181], v[202:205], v[20:23]
	v_mfma_f32_16x16x32_bf16 v[6:9], v[170:173], v[210:213], v[8:11]
	v_mfma_f32_16x16x32_bf16 v[2:5], v[178:181], v[210:213], v[2:5]
	v_mfma_f32_16x16x32_bf16 v[56:59], v[174:177], v[190:193], v[56:59]
	v_mfma_f32_16x16x32_bf16 v[52:55], v[182:185], v[190:193], v[52:55]
	v_mfma_f32_16x16x32_bf16 v[40:43], v[174:177], v[198:201], v[40:43]
	v_mfma_f32_16x16x32_bf16 v[36:39], v[182:185], v[198:201], v[36:39]
	v_mfma_f32_16x16x32_bf16 v[24:27], v[174:177], v[206:209], v[24:27]
	v_mfma_f32_16x16x32_bf16 v[20:23], v[182:185], v[206:209], v[20:23]
	v_mfma_f32_16x16x32_bf16 v[8:11], v[174:177], v[214:217], v[6:9]
	v_mfma_f32_16x16x32_bf16 v[4:7], v[182:185], v[214:217], v[2:5]
	s_barrier
	s_add_i32 s14, s92, 2
	s_add_u32 s54, s54, 0x100
	s_addc_u32 s55, s55, 0
	s_add_u32 s90, s90, 0x100
	s_addc_u32 s91, s91, 0
	s_cmp_gt_u32 s92, 29
	s_mov_b32 s92, s14
	s_cbranch_scc1 .LBB0_554

.LBB0_658:
	v_add_u32_e32 v1, s61, v201
	ds_read_b128 v[102:105], v1
	ds_read_b128 v[106:109], v1 offset:1024
	ds_read_b128 v[110:113], v1 offset:2048
	ds_read_b128 v[114:117], v1 offset:3072
	v_add_u32_e32 v1, s62, v201
	ds_read_b128 v[118:121], v1
	ds_read_b128 v[156:159], v1 offset:1024
	ds_read_b128 v[160:163], v1 offset:2048
	ds_read_b128 v[164:167], v1 offset:3072
	s_and_b64 s[48:49], exec, s[48:49]
	s_cselect_b32 s49, s27, s78
	s_cselect_b32 s48, s29, s73
	s_add_u32 s80, s80, 0x40000
	s_addc_u32 s81, s81, 0
	v_lshl_add_u64 v[2:3], s[80:81], 0, v[178:179]
	s_add_i32 m0, s41, 0xc000
	ds_read_b128 v[168:171], v207
	ds_read_b128 v[184:187], v207 offset:1024
	ds_read_b128 v[188:191], v207 offset:2048
	ds_read_b128 v[192:195], v207 offset:3072
	ds_read_b128 v[208:211], v207 offset:4096
	ds_read_b128 v[212:215], v207 offset:5120
	ds_read_b128 v[216:219], v207 offset:6144
	ds_read_b128 v[220:223], v207 offset:7168
	global_load_lds_dwordx4 v[2:3], off
	v_lshl_add_u64 v[2:3], s[80:81], 0, v[174:175]
	s_add_i32 m0, s41, 0xe000
	s_nop 0
	global_load_lds_dwordx4 v[2:3], off
	s_waitcnt vmcnt(8)
	s_waitcnt lgkmcnt(0)
	s_barrier
	s_waitcnt lgkmcnt(0)
	v_mfma_f32_16x16x32_bf16 v[152:155], v[102:105], v[168:171], v[152:155]
	v_mfma_f32_16x16x32_bf16 v[148:151], v[110:113], v[168:171], v[148:151]
	v_mfma_f32_16x16x32_bf16 v[144:147], v[102:105], v[188:191], v[144:147]
	v_mfma_f32_16x16x32_bf16 v[140:143], v[110:113], v[188:191], v[140:143]
	v_mfma_f32_16x16x32_bf16 v[136:139], v[102:105], v[208:211], v[136:139]
	v_mfma_f32_16x16x32_bf16 v[132:135], v[110:113], v[208:211], v[132:135]
	v_mfma_f32_16x16x32_bf16 v[128:131], v[102:105], v[216:219], v[128:131]
	v_mfma_f32_16x16x32_bf16 v[122:125], v[110:113], v[216:219], v[124:127]
	v_mfma_f32_16x16x32_bf16 v[152:155], v[106:109], v[184:187], v[152:155]
	v_mfma_f32_16x16x32_bf16 v[148:151], v[114:117], v[184:187], v[148:151]
	v_mfma_f32_16x16x32_bf16 v[144:147], v[106:109], v[192:195], v[144:147]
	v_mfma_f32_16x16x32_bf16 v[140:143], v[114:117], v[192:195], v[140:143]
	v_mfma_f32_16x16x32_bf16 v[136:139], v[106:109], v[212:215], v[136:139]
	v_mfma_f32_16x16x32_bf16 v[132:135], v[114:117], v[212:215], v[132:135]
	v_mfma_f32_16x16x32_bf16 v[128:131], v[106:109], v[220:223], v[128:131]
	v_mfma_f32_16x16x32_bf16 v[122:125], v[114:117], v[220:223], v[122:125]
	v_mfma_f32_16x16x32_bf16 v[64:67], v[118:121], v[168:171], v[64:67]
	v_mfma_f32_16x16x32_bf16 v[60:63], v[160:163], v[168:171], v[60:63]
	v_mfma_f32_16x16x32_bf16 v[56:59], v[118:121], v[188:191], v[56:59]
	v_mfma_f32_16x16x32_bf16 v[52:55], v[160:163], v[188:191], v[52:55]
	v_mfma_f32_16x16x32_bf16 v[48:51], v[118:121], v[208:211], v[48:51]
	v_mfma_f32_16x16x32_bf16 v[44:47], v[160:163], v[208:211], v[44:47]
	v_mfma_f32_16x16x32_bf16 v[40:43], v[118:121], v[216:219], v[40:43]
	v_mfma_f32_16x16x32_bf16 v[36:39], v[160:163], v[216:219], v[36:39]
	v_mfma_f32_16x16x32_bf16 v[64:67], v[156:159], v[184:187], v[64:67]
	v_mfma_f32_16x16x32_bf16 v[60:63], v[164:167], v[184:187], v[60:63]
	v_mfma_f32_16x16x32_bf16 v[56:59], v[156:159], v[192:195], v[56:59]
	v_mfma_f32_16x16x32_bf16 v[52:55], v[164:167], v[192:195], v[52:55]
	v_mfma_f32_16x16x32_bf16 v[48:51], v[156:159], v[212:215], v[48:51]
	v_mfma_f32_16x16x32_bf16 v[44:47], v[164:167], v[212:215], v[44:47]
	v_mfma_f32_16x16x32_bf16 v[40:43], v[156:159], v[220:223], v[40:43]
	v_mfma_f32_16x16x32_bf16 v[36:39], v[164:167], v[220:223], v[36:39]
	s_barrier
	s_add_i32 s6, s61, s53
	v_lshl_add_u64 v[196:197], s[48:49], 0, v[176:177]
	s_mov_b32 m0, s6
	ds_read_b128 v[168:171], v207 offset:16384
	ds_read_b128 v[184:187], v207 offset:17408
	ds_read_b128 v[188:191], v207 offset:18432
	ds_read_b128 v[192:195], v207 offset:19456
	ds_read_b128 v[208:211], v207 offset:20480
	ds_read_b128 v[212:215], v207 offset:21504
	ds_read_b128 v[216:219], v207 offset:22528
	ds_read_b128 v[220:223], v207 offset:23552
	global_load_lds_dwordx4 v[196:197], off
	s_add_i32 m0, s6, 0x2000
	s_add_u32 s80, s48, 0x80000
	v_lshl_add_u64 v[224:225], s[48:49], 0, v[172:173]
	s_addc_u32 s81, s49, 0
	s_add_i32 s6, s62, s53
	global_load_lds_dwordx4 v[224:225], off
	v_lshl_add_u64 v[2:3], s[80:81], 0, v[176:177]
	s_mov_b32 m0, s6
	v_lshl_add_u64 v[226:227], s[50:51], 0, v[178:179]
	global_load_lds_dwordx4 v[2:3], off
	v_lshl_add_u64 v[2:3], s[80:81], 0, v[172:173]
	s_add_i32 m0, s6, 0x2000
	v_lshl_add_u64 v[228:229], s[50:51], 0, v[174:175]
	global_load_lds_dwordx4 v[2:3], off
	s_mov_b32 m0, s41
	s_nop 0
	global_load_lds_dwordx4 v[226:227], off
	s_mov_b32 m0, s56
	s_nop 0
	global_load_lds_dwordx4 v[228:229], off
	s_waitcnt vmcnt(8)
	s_waitcnt lgkmcnt(0)
	s_barrier
	s_waitcnt lgkmcnt(0)
	v_mfma_f32_16x16x32_bf16 v[96:99], v[102:105], v[168:171], v[96:99]
	v_mfma_f32_16x16x32_bf16 v[92:95], v[110:113], v[168:171], v[92:95]
	v_mfma_f32_16x16x32_bf16 v[88:91], v[102:105], v[188:191], v[88:91]
	v_mfma_f32_16x16x32_bf16 v[84:87], v[110:113], v[188:191], v[84:87]
	v_mfma_f32_16x16x32_bf16 v[80:83], v[102:105], v[208:211], v[80:83]
	v_mfma_f32_16x16x32_bf16 v[76:79], v[110:113], v[208:211], v[76:79]
	v_mfma_f32_16x16x32_bf16 v[72:75], v[102:105], v[216:219], v[72:75]
	v_mfma_f32_16x16x32_bf16 v[68:71], v[110:113], v[216:219], v[68:71]
	v_mfma_f32_16x16x32_bf16 v[96:99], v[106:109], v[184:187], v[96:99]
	v_mfma_f32_16x16x32_bf16 v[92:95], v[114:117], v[184:187], v[92:95]
	v_mfma_f32_16x16x32_bf16 v[88:91], v[106:109], v[192:195], v[88:91]
	v_mfma_f32_16x16x32_bf16 v[84:87], v[114:117], v[192:195], v[84:87]
	v_mfma_f32_16x16x32_bf16 v[80:83], v[106:109], v[212:215], v[80:83]
	v_mfma_f32_16x16x32_bf16 v[76:79], v[114:117], v[212:215], v[76:79]
	v_mfma_f32_16x16x32_bf16 v[72:75], v[106:109], v[220:223], v[72:75]
	v_mfma_f32_16x16x32_bf16 v[68:71], v[114:117], v[220:223], v[68:71]
	v_mfma_f32_16x16x32_bf16 v[32:35], v[118:121], v[168:171], v[32:35]
	v_mfma_f32_16x16x32_bf16 v[28:31], v[160:163], v[168:171], v[28:31]
	v_mfma_f32_16x16x32_bf16 v[24:27], v[118:121], v[188:191], v[24:27]
	v_mfma_f32_16x16x32_bf16 v[20:23], v[160:163], v[188:191], v[20:23]
	v_mfma_f32_16x16x32_bf16 v[16:19], v[118:121], v[208:211], v[16:19]
	v_mfma_f32_16x16x32_bf16 v[12:15], v[160:163], v[208:211], v[12:15]
	v_mfma_f32_16x16x32_bf16 v[8:11], v[118:121], v[216:219], v[8:11]
	v_mfma_f32_16x16x32_bf16 v[2:5], v[160:163], v[216:219], v[4:7]
	v_mfma_f32_16x16x32_bf16 v[32:35], v[156:159], v[184:187], v[32:35]
	v_mfma_f32_16x16x32_bf16 v[28:31], v[164:167], v[184:187], v[28:31]
	v_mfma_f32_16x16x32_bf16 v[24:27], v[156:159], v[192:195], v[24:27]
	v_mfma_f32_16x16x32_bf16 v[20:23], v[164:167], v[192:195], v[20:23]
	v_mfma_f32_16x16x32_bf16 v[16:19], v[156:159], v[212:215], v[16:19]
	v_mfma_f32_16x16x32_bf16 v[12:15], v[164:167], v[212:215], v[12:15]
	v_mfma_f32_16x16x32_bf16 v[8:11], v[156:159], v[220:223], v[8:11]
	v_mfma_f32_16x16x32_bf16 v[2:5], v[164:167], v[220:223], v[2:5]
	s_barrier
	s_add_i32 s6, 0, 0x18000
	v_add_u32_e32 v1, s6, v201
	s_add_i32 s80, 0, 0x1c000
	ds_read_b128 v[102:105], v1
	ds_read_b128 v[106:109], v1 offset:1024
	ds_read_b128 v[110:113], v1 offset:2048
	ds_read_b128 v[114:117], v1 offset:3072
	v_add_u32_e32 v1, s80, v201
	ds_read_b128 v[118:121], v1
	ds_read_b128 v[156:159], v1 offset:1024
	ds_read_b128 v[160:163], v1 offset:2048
	ds_read_b128 v[164:167], v1 offset:3072
	s_add_u32 s50, s50, 0x40000
	s_addc_u32 s51, s51, 0
	s_mov_b32 m0, s57
	v_lshl_add_u64 v[6:7], s[50:51], 0, v[178:179]
	ds_read_b128 v[168:171], v207 offset:32768
	ds_read_b128 v[184:187], v207 offset:33792
	ds_read_b128 v[188:191], v207 offset:34816
	ds_read_b128 v[192:195], v207 offset:35840
	ds_read_b128 v[208:211], v207 offset:36864
	ds_read_b128 v[212:215], v207 offset:37888
	ds_read_b128 v[216:219], v207 offset:38912
	ds_read_b128 v[220:223], v207 offset:39936
	global_load_lds_dwordx4 v[6:7], off
	v_lshl_add_u64 v[6:7], s[50:51], 0, v[174:175]
	s_mov_b32 m0, s58
	s_nop 0
	global_load_lds_dwordx4 v[6:7], off
	s_waitcnt vmcnt(8)
	s_waitcnt lgkmcnt(0)
	s_barrier
	s_waitcnt lgkmcnt(0)
	v_mfma_f32_16x16x32_bf16 v[152:155], v[102:105], v[168:171], v[152:155]
	v_mfma_f32_16x16x32_bf16 v[148:151], v[110:113], v[168:171], v[148:151]
	v_mfma_f32_16x16x32_bf16 v[144:147], v[102:105], v[188:191], v[144:147]
	v_mfma_f32_16x16x32_bf16 v[140:143], v[110:113], v[188:191], v[140:143]
	v_mfma_f32_16x16x32_bf16 v[136:139], v[102:105], v[208:211], v[136:139]
	v_mfma_f32_16x16x32_bf16 v[132:135], v[110:113], v[208:211], v[132:135]
	v_mfma_f32_16x16x32_bf16 v[126:129], v[102:105], v[216:219], v[128:131]
	v_mfma_f32_16x16x32_bf16 v[122:125], v[110:113], v[216:219], v[122:125]
	v_mfma_f32_16x16x32_bf16 v[152:155], v[106:109], v[184:187], v[152:155]
	v_mfma_f32_16x16x32_bf16 v[148:151], v[114:117], v[184:187], v[148:151]
	v_mfma_f32_16x16x32_bf16 v[144:147], v[106:109], v[192:195], v[144:147]
	v_mfma_f32_16x16x32_bf16 v[140:143], v[114:117], v[192:195], v[140:143]
	v_mfma_f32_16x16x32_bf16 v[136:139], v[106:109], v[212:215], v[136:139]
	v_mfma_f32_16x16x32_bf16 v[132:135], v[114:117], v[212:215], v[132:135]
	v_mfma_f32_16x16x32_bf16 v[128:131], v[106:109], v[220:223], v[126:129]
	v_mfma_f32_16x16x32_bf16 v[124:127], v[114:117], v[220:223], v[122:125]
	v_mfma_f32_16x16x32_bf16 v[64:67], v[118:121], v[168:171], v[64:67]
	v_mfma_f32_16x16x32_bf16 v[60:63], v[160:163], v[168:171], v[60:63]
	v_mfma_f32_16x16x32_bf16 v[56:59], v[118:121], v[188:191], v[56:59]
	v_mfma_f32_16x16x32_bf16 v[52:55], v[160:163], v[188:191], v[52:55]
	v_mfma_f32_16x16x32_bf16 v[48:51], v[118:121], v[208:211], v[48:51]
	v_mfma_f32_16x16x32_bf16 v[44:47], v[160:163], v[208:211], v[44:47]
	v_mfma_f32_16x16x32_bf16 v[40:43], v[118:121], v[216:219], v[40:43]
	v_mfma_f32_16x16x32_bf16 v[36:39], v[160:163], v[216:219], v[36:39]
	v_mfma_f32_16x16x32_bf16 v[64:67], v[156:159], v[184:187], v[64:67]
	v_mfma_f32_16x16x32_bf16 v[60:63], v[164:167], v[184:187], v[60:63]
	v_mfma_f32_16x16x32_bf16 v[56:59], v[156:159], v[192:195], v[56:59]
	v_mfma_f32_16x16x32_bf16 v[52:55], v[164:167], v[192:195], v[52:55]
	v_mfma_f32_16x16x32_bf16 v[48:51], v[156:159], v[212:215], v[48:51]
	v_mfma_f32_16x16x32_bf16 v[44:47], v[164:167], v[212:215], v[44:47]
	v_mfma_f32_16x16x32_bf16 v[40:43], v[156:159], v[220:223], v[40:43]
	v_mfma_f32_16x16x32_bf16 v[36:39], v[164:167], v[220:223], v[36:39]
	s_barrier
	s_add_i32 s6, s6, s53
	v_lshl_add_u64 v[6:7], v[196:197], 0, s[14:15]
	s_mov_b32 m0, s6
	ds_read_b128 v[168:171], v207 offset:49152
	ds_read_b128 v[184:187], v207 offset:50176
	ds_read_b128 v[188:191], v207 offset:51200
	ds_read_b128 v[192:195], v207 offset:52224
	ds_read_b128 v[208:211], v207 offset:53248
	ds_read_b128 v[212:215], v207 offset:54272
	ds_read_b128 v[216:219], v207 offset:55296
	ds_read_b128 v[220:223], v207 offset:56320
	global_load_lds_dwordx4 v[6:7], off
	s_add_i32 m0, s6, 0x2000
	s_add_u32 s48, s48, 0x80080
	v_lshl_add_u64 v[6:7], v[224:225], 0, s[14:15]
	s_addc_u32 s49, s49, 0
	s_add_i32 s6, s80, s53
	global_load_lds_dwordx4 v[6:7], off
	v_lshl_add_u64 v[6:7], s[48:49], 0, v[176:177]
	s_mov_b32 m0, s6
	s_nop 0
	global_load_lds_dwordx4 v[6:7], off
	v_lshl_add_u64 v[6:7], s[48:49], 0, v[172:173]
	s_add_i32 m0, s6, 0x2000
	s_nop 0
	global_load_lds_dwordx4 v[6:7], off
	v_lshl_add_u64 v[6:7], v[226:227], 0, s[14:15]
	s_mov_b32 m0, s59
	s_nop 0
	global_load_lds_dwordx4 v[6:7], off
	v_lshl_add_u64 v[6:7], v[228:229], 0, s[14:15]
	s_mov_b32 m0, s60
	s_nop 0
	global_load_lds_dwordx4 v[6:7], off
	s_waitcnt vmcnt(8)
	s_waitcnt lgkmcnt(0)
	s_barrier
	s_waitcnt lgkmcnt(0)
	v_mfma_f32_16x16x32_bf16 v[96:99], v[102:105], v[168:171], v[96:99]
	v_mfma_f32_16x16x32_bf16 v[92:95], v[110:113], v[168:171], v[92:95]
	v_mfma_f32_16x16x32_bf16 v[88:91], v[102:105], v[188:191], v[88:91]
	v_mfma_f32_16x16x32_bf16 v[84:87], v[110:113], v[188:191], v[84:87]
	v_mfma_f32_16x16x32_bf16 v[80:83], v[102:105], v[208:211], v[80:83]
	v_mfma_f32_16x16x32_bf16 v[76:79], v[110:113], v[208:211], v[76:79]
	v_mfma_f32_16x16x32_bf16 v[72:75], v[102:105], v[216:219], v[72:75]
	v_mfma_f32_16x16x32_bf16 v[68:71], v[110:113], v[216:219], v[68:71]
	v_mfma_f32_16x16x32_bf16 v[96:99], v[106:109], v[184:187], v[96:99]
	v_mfma_f32_16x16x32_bf16 v[92:95], v[114:117], v[184:187], v[92:95]
	v_mfma_f32_16x16x32_bf16 v[88:91], v[106:109], v[192:195], v[88:91]
	v_mfma_f32_16x16x32_bf16 v[84:87], v[114:117], v[192:195], v[84:87]
	v_mfma_f32_16x16x32_bf16 v[80:83], v[106:109], v[212:215], v[80:83]
	v_mfma_f32_16x16x32_bf16 v[76:79], v[114:117], v[212:215], v[76:79]
	v_mfma_f32_16x16x32_bf16 v[72:75], v[106:109], v[220:223], v[72:75]
	v_mfma_f32_16x16x32_bf16 v[68:71], v[114:117], v[220:223], v[68:71]
	v_mfma_f32_16x16x32_bf16 v[32:35], v[118:121], v[168:171], v[32:35]
	v_mfma_f32_16x16x32_bf16 v[28:31], v[160:163], v[168:171], v[28:31]
	v_mfma_f32_16x16x32_bf16 v[24:27], v[118:121], v[188:191], v[24:27]
	v_mfma_f32_16x16x32_bf16 v[20:23], v[160:163], v[188:191], v[20:23]
	v_mfma_f32_16x16x32_bf16 v[16:19], v[118:121], v[208:211], v[16:19]
	v_mfma_f32_16x16x32_bf16 v[12:15], v[160:163], v[208:211], v[12:15]
	v_mfma_f32_16x16x32_bf16 v[6:9], v[118:121], v[216:219], v[8:11]
	v_mfma_f32_16x16x32_bf16 v[2:5], v[160:163], v[216:219], v[2:5]
	v_mfma_f32_16x16x32_bf16 v[32:35], v[156:159], v[184:187], v[32:35]
	v_mfma_f32_16x16x32_bf16 v[28:31], v[164:167], v[184:187], v[28:31]
	v_mfma_f32_16x16x32_bf16 v[24:27], v[156:159], v[192:195], v[24:27]
	v_mfma_f32_16x16x32_bf16 v[20:23], v[164:167], v[192:195], v[20:23]
	v_mfma_f32_16x16x32_bf16 v[16:19], v[156:159], v[212:215], v[16:19]
	v_mfma_f32_16x16x32_bf16 v[12:15], v[164:167], v[212:215], v[12:15]
	v_mfma_f32_16x16x32_bf16 v[8:11], v[156:159], v[220:223], v[6:9]
	v_mfma_f32_16x16x32_bf16 v[4:7], v[164:167], v[220:223], v[2:5]
	s_barrier
	s_add_i32 s6, s79, 2
	s_add_u32 s44, s44, 0x100
	s_addc_u32 s45, s45, 0
	s_add_u32 s73, s73, 0x100
	s_addc_u32 s78, s78, 0
	s_cmp_gt_u32 s79, 29
	s_cbranch_scc1 .LBB0_660
	s_mov_b32 s79, s6
	s_cmp_lg_u32 s79, 16
	s_cbranch_scc0 .LBB0_652
	s_branch .LBB0_653
